# v15 + P9 epilogue packed f32 weighting (pk_mul/pk_fma) + P1 forget-gate log: dead denormal/non-finite branches removed, single-multiply ln2 (13->2 instrs per element) + rcp wait-state slots filled
# speedup vs baseline: 1.0023x; 1.0014x over previous
; DI bf16x8 pack8(const f32x4& a, const f32x4& b) { v4u w; w.x = pk2(a[0], a[1]); w.y = pk2(a[2], a[3]); w.z = pk2(b[0], b[1]); w.w = pk2(b[2], b[3]); return __builtin_bit_cast(bf16x8, w); }
;     DI void operator()(const f32x4 (&acc)[2][2][4][2], const pg8::Unit& u, int wr, int wc, int fr, int fq) const {
;         const int ty = u.pn >> 3, cbase = (u.pn & 7) * 256 + wc * 32 + 8 * fq;
;         if (ty == 1) {
;             f32x4 lbv[2][2];
; #pragma unroll
;             for (int bj = 0; bj < 2; ++bj) { lbv[bj][0] = *(const f32x4*)(lb0 + cbase + bj * 128); lbv[bj][1] = *(const f32x4*)(lb0 + cbase + bj * 128 + 4); }
;             EPI_LOOP_BEGIN
; #pragma unroll
;                 for (int bj = 0; bj < 2; ++bj) { const size_t o = (size_t)row * D + cbase + bj * 128; f32x4 lg[2], kk[2];
; #pragma unroll
;                     for (int n = 0; n < 2; ++n)
; #pragma unroll
;                         for (int e = 0; e < 4; ++e) { const float f = fminf(fmaxf(acc[ai][bj][m][n][e], -30.f), 30.f), lb = lbv[bj][n][e], ef = __expf(-f), sg = 1.f / (1.f + ef), sgn = ef / (1.f + ef);
;                             lg[n][e] = __logf(lb + (1.f - lb) * sg); kk[n][e] = (1.f - lb) * sgn; }
;                     *(f32x4*)(lf + o) = lg[0]; *(f32x4*)(lf + o + 4) = lg[1]; *(bf16x8*)(zq + (size_t)T * D + o) = pack8(kk[0], kk[1]); }
.LBB0_268:
	s_and_b64 vcc, exec, s[6:7]
	s_cbranch_vccz .LBB0_267
	v_ashrrev_i32_e32 v161, 31, v160
	v_lshl_add_u64 v[76:77], v[160:161], 2, s[22:23]
	global_load_dwordx4 v[88:91], v[76:77], off
	global_load_dwordx4 v[80:83], v[76:77], off offset:16
	v_max_f32_e32 v68, v140, v140
	v_max_f32_e32 v69, v141, v141
	v_med3_f32 v141, v68, s68, v188
	v_med3_f32 v162, v69, s68, v188
	v_mul_f32_e32 v141, 0xbfb8aa3b, v141
	v_mul_f32_e32 v163, 0xbfb8aa3b, v162
	s_lshl_b32 s45, s8, 8
	v_exp_f32_e32 v162, v141
	v_exp_f32_e32 v163, v163
	v_add_u32_e32 v140, s45, v175
	v_ashrrev_i32_e32 v141, 31, v140
	v_lshlrev_b64 v[140:141], 11, v[140:141]
	v_lshl_add_u64 v[168:169], v[140:141], 0, v[160:161]
	v_pk_add_f32 v[140:141], v[162:163], 1.0 op_sel_hi:[1,0]
	v_max_f32_e32 v142, v142, v142
	v_rcp_f32_e32 v170, v140
	v_rcp_f32_e32 v171, v141
	v_rcp_f32_e32 v164, v141
	s_nop 0
	v_mul_f32_e32 v165, v163, v164
	v_rcp_f32_e32 v141, v140
	s_nop 0
	v_mul_f32_e32 v164, v162, v141
	v_med3_f32 v142, v142, s68, v188
	v_mul_f32_e32 v142, 0xbfb8aa3b, v142
	v_max_f32_e32 v136, v136, v136
	v_med3_f32 v136, v136, s68, v188
	v_mul_f32_e32 v136, 0xbfb8aa3b, v136
	v_max_f32_e32 v138, v138, v138
	v_max_f32_e32 v139, v139, v139
	v_med3_f32 v138, v138, s68, v188
	s_waitcnt vmcnt(0)
	v_pk_add_f32 v[166:167], v[88:89], 1.0 op_sel_hi:[1,0] neg_lo:[1,0] neg_hi:[1,0]
	v_med3_f32 v139, v139, s68, v188
	v_fma_f32 v140, v170, v166, v88
	v_exp_f32_e32 v170, v142
	v_max_f32_e32 v142, v143, v143
	v_log_f32_e32 v140, v140
	v_fma_f32 v141, v171, v167, v89
	v_med3_f32 v142, v142, s68, v188
	v_mul_f32_e32 v142, 0xbfb8aa3b, v142
	v_exp_f32_e32 v171, v142
	v_log_f32_e32 v141, v141
	v_pk_add_f32 v[190:191], v[170:171], 1.0 op_sel_hi:[1,0]
	v_mul_f32_e32 v140, 0x3f317218, v140
	v_mul_f32_e32 v138, 0xbfb8aa3b, v138
	v_mul_f32_e32 v139, 0xbfb8aa3b, v139
	v_mul_f32_e32 v141, 0x3f317218, v141
	v_rcp_f32_e32 v142, v190
	v_pk_add_f32 v[162:163], v[90:91], 1.0 op_sel_hi:[1,0] neg_lo:[1,0] neg_hi:[1,0]
	v_pk_mul_f32 v[172:173], v[164:165], v[166:167]
	v_fma_f32 v142, v142, v162, v90
	v_exp_f32_e32 v138, v138
	v_exp_f32_e32 v139, v139
	v_log_f32_e32 v142, v142
	global_load_dwordx4 v[68:71], v[76:77], off offset:528
	s_nop 0
	global_load_dwordx4 v[76:79], v[76:77], off offset:512
	v_mul_f32_e32 v142, 0x3f317218, v142
	v_rcp_f32_e32 v143, v191
	s_nop 0
	v_fma_f32 v143, v143, v163, v91
	v_rcp_f32_e32 v165, v191
	v_rcp_f32_e32 v164, v190
	v_mul_f32_e32 v165, v171, v165
	v_mul_f32_e32 v164, v170, v164
	v_max_f32_e32 v132, v132, v132
	v_exp_f32_e32 v170, v136
	v_max_f32_e32 v136, v137, v137
	v_med3_f32 v136, v136, s68, v188
	v_mul_f32_e32 v136, 0xbfb8aa3b, v136
	v_exp_f32_e32 v171, v136
	v_log_f32_e32 v143, v143
	v_med3_f32 v132, v132, s68, v188
	v_mul_f32_e32 v132, 0xbfb8aa3b, v132
	v_pk_add_f32 v[192:193], v[170:171], 1.0 op_sel_hi:[1,0]
	v_max_f32_e32 v134, v134, v134
	v_med3_f32 v134, v134, s68, v188
	v_mul_f32_e32 v143, 0x3f317218, v143
	v_rcp_f32_e32 v190, v192
	v_pk_add_f32 v[136:137], v[80:81], 1.0 op_sel_hi:[1,0] neg_lo:[1,0] neg_hi:[1,0]
	v_pk_mul_f32 v[194:195], v[164:165], v[162:163]
	v_fma_f32 v190, v190, v136, v80
	v_mul_f32_e32 v134, 0xbfb8aa3b, v134
	v_max_f32_e32 v128, v128, v128
	v_log_f32_e32 v190, v190
	v_med3_f32 v128, v128, s68, v188
	v_mul_f32_e32 v128, 0xbfb8aa3b, v128
	v_mul_f32_e32 v164, 0x3f317218, v190
	v_mov_b32_e32 v190, v164
	v_rcp_f32_e32 v164, v193
	s_nop 0
	v_fma_f32 v164, v164, v137, v81
	v_rcp_f32_e32 v165, v193
	s_nop 0
	v_mul_f32_e32 v171, v171, v165
	v_rcp_f32_e32 v165, v192
	s_nop 0
	v_mul_f32_e32 v170, v170, v165
	v_log_f32_e32 v164, v164
	v_pk_add_f32 v[196:197], v[138:139], 1.0 op_sel_hi:[1,0]
	v_max_f32_e32 v130, v130, v130
	v_med3_f32 v130, v130, s68, v188
	v_mul_f32_e32 v130, 0xbfb8aa3b, v130
	v_mul_f32_e32 v193, 0x3f317218, v164
	v_rcp_f32_e32 v191, v196
	v_pk_add_f32 v[164:165], v[82:83], 1.0 op_sel_hi:[1,0] neg_lo:[1,0] neg_hi:[1,0]
	v_pk_mul_f32 v[198:199], v[170:171], v[136:137]
	v_fma_f32 v191, v191, v164, v82
	v_max_f32_e32 v124, v124, v124
	v_med3_f32 v124, v124, s68, v188
	v_log_f32_e32 v192, v191
	v_mov_b32_e32 v191, v193
	v_mul_f32_e32 v124, 0xbfb8aa3b, v124
	v_max_f32_e32 v126, v126, v126
	v_mul_f32_e32 v170, 0x3f317218, v192
	v_mov_b32_e32 v192, v170
	v_rcp_f32_e32 v170, v197
	v_rcp_f32_e32 v171, v196
	v_mul_f32_e32 v139, v139, v170
	v_mul_f32_e32 v138, v138, v171
	v_rcp_f32_e32 v193, v197
	s_nop 0
	v_fma_f32 v193, v193, v165, v83
	v_pk_mul_f32 v[196:197], v[138:139], v[164:165]
	v_lshl_add_u64 v[170:171], v[168:169], 2, s[18:19]
	v_log_f32_e32 v193, v193
	v_exp_f32_e32 v200, v132
	v_max_f32_e32 v132, v133, v133
	v_med3_f32 v132, v132, s68, v188
	v_mul_f32_e32 v132, 0xbfb8aa3b, v132
	v_exp_f32_e32 v201, v132
	v_med3_f32 v126, v126, s68, v188
	v_mul_f32_e32 v138, 0x3f317218, v193
	v_mov_b32_e32 v193, v138
	global_store_dwordx4 v[170:171], v[140:143], off
	global_store_dwordx4 v[170:171], v[190:193], off offset:16
	v_mul_f32_e32 v126, 0xbfb8aa3b, v126
	v_pk_add_f32 v[140:141], v[200:201], 1.0 op_sel_hi:[1,0]
	v_cvt_pk_bf16_f32 v190, v172, v173
	v_cvt_pk_bf16_f32 v191, v194, v195
	v_cvt_pk_bf16_f32 v192, v198, v199
	v_cvt_pk_bf16_f32 v193, v196, v197
	v_rcp_f32_e32 v132, v140
	s_waitcnt vmcnt(2)
; DI bf16x8 pack8(const f32x4& a, const f32x4& b) { v4u w; w.x = pk2(a[0], a[1]); w.y = pk2(a[2], a[3]); w.z = pk2(b[0], b[1]); w.w = pk2(b[2], b[3]); return __builtin_bit_cast(bf16x8, w); }
;     DI void operator()(const f32x4 (&acc)[2][2][4][2], const pg8::Unit& u, int wr, int wc, int fr, int fq) const {
;     ...
;                 for (int bj = 0; bj < 2; ++bj) { const size_t o = (size_t)row * D + cbase + bj * 128; f32x4 lg[2], kk[2];
; #pragma unroll
;                     for (int n = 0; n < 2; ++n)
; #pragma unroll
;                         for (int e = 0; e < 4; ++e) { const float f = fminf(fmaxf(acc[ai][bj][m][n][e], -30.f), 30.f), lb = lbv[bj][n][e], ef = __expf(-f), sg = 1.f / (1.f + ef), sgn = ef / (1.f + ef);
;                             lg[n][e] = __logf(lb + (1.f - lb) * sg); kk[n][e] = (1.f - lb) * sgn; }
;                     *(f32x4*)(lf + o) = lg[0]; *(f32x4*)(lf + o + 4) = lg[1]; *(bf16x8*)(zq + (size_t)T * D + o) = pack8(kk[0], kk[1]); }
	v_pk_add_f32 v[138:139], v[76:77], 1.0 op_sel_hi:[1,0] neg_lo:[1,0] neg_hi:[1,0]
	v_lshl_add_u64 v[142:143], v[168:169], 1, s[42:43]
	v_fma_f32 v132, v132, v138, v76
	s_nop 0
	s_nop 0
	v_log_f32_e32 v132, v132
	global_store_dwordx4 v[142:143], v[190:193], off
	v_max_f32_e32 v120, v120, v120
	v_med3_f32 v120, v120, s68, v188
	v_mul_f32_e32 v120, 0xbfb8aa3b, v120
	v_mul_f32_e32 v132, 0x3f317218, v132
	v_rcp_f32_e32 v133, v141
	v_max_f32_e32 v122, v122, v122
	v_mul_f32_e32 v169, v201, v133
	v_max_f32_e32 v123, v123, v123
	v_exp_f32_e32 v172, v134
	v_max_f32_e32 v134, v135, v135
	v_med3_f32 v134, v134, s68, v188
	v_mul_f32_e32 v134, 0xbfb8aa3b, v134
	v_exp_f32_e32 v173, v134
	v_rcp_f32_e32 v141, v141
	s_nop 0
	v_fma_f32 v141, v141, v139, v77
	v_pk_add_f32 v[190:191], v[172:173], 1.0 op_sel_hi:[1,0]
	v_med3_f32 v122, v122, s68, v188
	v_rcp_f32_e32 v133, v140
	s_nop 0
	v_mul_f32_e32 v168, v200, v133
	v_log_f32_e32 v192, v141
	v_rcp_f32_e32 v134, v190
	v_pk_add_f32 v[140:141], v[78:79], 1.0 op_sel_hi:[1,0] neg_lo:[1,0] neg_hi:[1,0]
	v_fma_f32 v134, v134, v140, v78
	v_log_f32_e32 v134, v134
	v_pk_mul_f32 v[168:169], v[168:169], v[138:139]
	v_mul_f32_e32 v133, 0x3f317218, v192
	v_med3_f32 v123, v123, s68, v188
	v_mul_f32_e32 v122, 0xbfb8aa3b, v122
	v_mul_f32_e32 v134, 0x3f317218, v134
	v_rcp_f32_e32 v135, v191
	v_mul_f32_e32 v123, 0xbfb8aa3b, v123
	v_mul_f32_e32 v173, v173, v135
	v_rcp_f32_e32 v135, v190
	v_rcp_f32_e32 v191, v191
	v_mul_f32_e32 v172, v172, v135
	v_fma_f32 v191, v191, v141, v79
	v_pk_mul_f32 v[172:173], v[172:173], v[140:141]
	v_exp_f32_e32 v122, v122
	v_exp_f32_e32 v192, v128
	v_max_f32_e32 v128, v129, v129
	v_med3_f32 v128, v128, s68, v188
	v_mul_f32_e32 v128, 0xbfb8aa3b, v128
	v_exp_f32_e32 v193, v128
	v_log_f32_e32 v191, v191
	v_exp_f32_e32 v123, v123
	v_max_f32_e32 v116, v116, v116
	v_pk_add_f32 v[194:195], v[192:193], 1.0 op_sel_hi:[1,0]
	v_rcp_f32_e32 v135, v194
	v_pk_add_f32 v[128:129], v[68:69], 1.0 op_sel_hi:[1,0] neg_lo:[1,0] neg_hi:[1,0]
	v_fma_f32 v135, v135, v128, v68
	v_med3_f32 v116, v116, s68, v188
	v_mul_f32_e32 v116, 0xbfb8aa3b, v116
	v_log_f32_e32 v196, v135
	v_mul_f32_e32 v135, 0x3f317218, v191
	v_max_f32_e32 v118, v118, v118
	v_med3_f32 v118, v118, s68, v188
	v_mul_f32_e32 v190, 0x3f317218, v196
	v_rcp_f32_e32 v191, v195
	v_mul_f32_e32 v118, 0xbfb8aa3b, v118
	v_mul_f32_e32 v193, v193, v191
	v_rcp_f32_e32 v191, v194
	v_rcp_f32_e32 v195, v195
	v_mul_f32_e32 v192, v192, v191
	v_fma_f32 v195, v195, v129, v69
	v_max_f32_e32 v112, v112, v112
	v_med3_f32 v112, v112, s68, v188
	v_exp_f32_e32 v196, v130
	v_max_f32_e32 v130, v131, v131
	v_med3_f32 v130, v130, s68, v188
	v_mul_f32_e32 v130, 0xbfb8aa3b, v130
	v_exp_f32_e32 v197, v130
	v_log_f32_e32 v200, v195
	v_pk_mul_f32 v[194:195], v[192:193], v[128:129]
	v_mul_f32_e32 v112, 0xbfb8aa3b, v112
	v_pk_add_f32 v[198:199], v[196:197], 1.0 op_sel_hi:[1,0]
	v_rcp_f32_e32 v191, v198
	v_pk_add_f32 v[130:131], v[70:71], 1.0 op_sel_hi:[1,0] neg_lo:[1,0] neg_hi:[1,0]
	v_fma_f32 v191, v191, v130, v70
	v_max_f32_e32 v114, v114, v114
	v_max_f32_e32 v115, v115, v115
	v_log_f32_e32 v193, v191
	v_mul_f32_e32 v191, 0x3f317218, v200
	v_med3_f32 v114, v114, s68, v188
	v_med3_f32 v115, v115, s68, v188
	v_mul_f32_e32 v192, 0x3f317218, v193
	v_rcp_f32_e32 v193, v199
	v_rcp_f32_e32 v200, v198
	v_mul_f32_e32 v197, v197, v193
	v_mul_f32_e32 v196, v196, v200
	v_rcp_f32_e32 v201, v199
	s_nop 0
	v_fma_f32 v201, v201, v131, v71
	v_pk_mul_f32 v[196:197], v[196:197], v[130:131]
	v_mul_f32_e32 v114, 0xbfb8aa3b, v114
	v_log_f32_e32 v201, v201
	v_mul_f32_e32 v115, 0xbfb8aa3b, v115
	v_exp_f32_e32 v114, v114
	v_exp_f32_e32 v115, v115
	v_max_f32_e32 v108, v108, v108
	v_mul_f32_e32 v193, 0x3f317218, v201
	global_store_dwordx4 v[170:171], v[132:135], off offset:512
	global_store_dwordx4 v[170:171], v[190:193], off offset:528
	v_exp_f32_e32 v170, v124
	v_max_f32_e32 v124, v125, v125
	v_med3_f32 v124, v124, s68, v188
	v_mul_f32_e32 v124, 0xbfb8aa3b, v124
	v_exp_f32_e32 v171, v124
	v_cvt_pk_bf16_f32 v132, v168, v169
	v_cvt_pk_bf16_f32 v133, v172, v173
	v_cvt_pk_bf16_f32 v134, v194, v195
	v_pk_add_f32 v[168:169], v[170:171], 1.0 op_sel_hi:[1,0]
	v_cvt_pk_bf16_f32 v135, v196, v197
	global_store_dwordx4 v[142:143], v[132:135], off offset:256
	v_add_u32_e32 v124, s45, v178
	v_med3_f32 v108, v108, s68, v188
	v_rcp_f32_e32 v125, v168
	s_nop 0
	v_fma_f32 v125, v125, v166, v88
	v_mul_f32_e32 v108, 0xbfb8aa3b, v108
	v_max_f32_e32 v110, v110, v110
	v_log_f32_e32 v134, v125
	v_ashrrev_i32_e32 v125, 31, v124
	v_lshlrev_b64 v[124:125], 11, v[124:125]
	v_lshl_add_u64 v[132:133], v[124:125], 0, v[160:161]
	v_med3_f32 v110, v110, s68, v188
	v_mul_f32_e32 v110, 0xbfb8aa3b, v110
	v_mul_f32_e32 v124, 0x3f317218, v134
	v_rcp_f32_e32 v125, v169
	v_max_f32_e32 v104, v104, v104
	v_mul_f32_e32 v135, v171, v125
	v_med3_f32 v104, v104, s68, v188
	v_rcp_f32_e32 v134, v169
	s_nop 0
	v_fma_f32 v134, v134, v167, v89
	v_mul_f32_e32 v104, 0xbfb8aa3b, v104
	v_max_f32_e32 v106, v106, v106
	v_exp_f32_e32 v142, v126
	v_max_f32_e32 v126, v127, v127
	v_med3_f32 v126, v126, s68, v188
	v_mul_f32_e32 v126, 0xbfb8aa3b, v126
	v_exp_f32_e32 v143, v126
	v_log_f32_e32 v171, v134
	v_rcp_f32_e32 v125, v168
	s_nop 0
	v_mul_f32_e32 v134, v170, v125
	v_pk_mul_f32 v[134:135], v[134:135], v[166:167]
	v_pk_add_f32 v[168:169], v[142:143], 1.0 op_sel_hi:[1,0]
	v_rcp_f32_e32 v126, v168
	s_nop 0
	v_fma_f32 v126, v126, v162, v90
	v_max_f32_e32 v107, v107, v107
	v_log_f32_e32 v126, v126
	v_mul_f32_e32 v125, 0x3f317218, v171
	v_med3_f32 v106, v106, s68, v188
	v_med3_f32 v107, v107, s68, v188
	v_mul_f32_e32 v126, 0x3f317218, v126
	v_rcp_f32_e32 v127, v169
; DI bf16x8 pack8(const f32x4& a, const f32x4& b) { v4u w; w.x = pk2(a[0], a[1]); w.y = pk2(a[2], a[3]); w.z = pk2(b[0], b[1]); w.w = pk2(b[2], b[3]); return __builtin_bit_cast(bf16x8, w); }
;     DI void operator()(const f32x4 (&acc)[2][2][4][2], const pg8::Unit& u, int wr, int wc, int fr, int fq) const {
;     ...
;             EPI_LOOP_BEGIN
; #pragma unroll
;                 for (int bj = 0; bj < 2; ++bj) { const size_t o = (size_t)row * D + cbase + bj * 128; f32x4 lg[2], kk[2];
; #pragma unroll
;                     for (int n = 0; n < 2; ++n)
; #pragma unroll
;                         for (int e = 0; e < 4; ++e) { const float f = fminf(fmaxf(acc[ai][bj][m][n][e], -30.f), 30.f), lb = lbv[bj][n][e], ef = __expf(-f), sg = 1.f / (1.f + ef), sgn = ef / (1.f + ef);
;                             lg[n][e] = __logf(lb + (1.f - lb) * sg); kk[n][e] = (1.f - lb) * sgn; }
;                     *(f32x4*)(lf + o) = lg[0]; *(f32x4*)(lf + o + 4) = lg[1]; *(bf16x8*)(zq + (size_t)T * D + o) = pack8(kk[0], kk[1]); }
;             EPI_LOOP_END
	v_mul_f32_e32 v106, 0xbfb8aa3b, v106
	v_mul_f32_e32 v143, v143, v127
	v_rcp_f32_e32 v127, v168
	v_rcp_f32_e32 v169, v169
	v_mul_f32_e32 v142, v142, v127
	v_fma_f32 v169, v169, v163, v91
	v_mul_f32_e32 v107, 0xbfb8aa3b, v107
	v_exp_f32_e32 v106, v106
	v_exp_f32_e32 v170, v120
	v_max_f32_e32 v120, v121, v121
	v_med3_f32 v120, v120, s68, v188
	v_mul_f32_e32 v120, 0xbfb8aa3b, v120
	v_exp_f32_e32 v171, v120
	v_pk_mul_f32 v[120:121], v[142:143], v[162:163]
	v_log_f32_e32 v169, v169
	v_exp_f32_e32 v107, v107
	v_pk_add_f32 v[142:143], v[170:171], 1.0 op_sel_hi:[1,0]
	v_max_f32_e32 v100, v100, v100
	v_rcp_f32_e32 v168, v142
	s_nop 0
	v_fma_f32 v168, v168, v136, v80
	v_log_f32_e32 v168, v168
	v_mul_f32_e32 v127, 0x3f317218, v169
	v_med3_f32 v100, v100, s68, v188
	v_mul_f32_e32 v100, 0xbfb8aa3b, v100
	v_mul_f32_e32 v168, 0x3f317218, v168
	v_rcp_f32_e32 v169, v143
	v_max_f32_e32 v102, v102, v102
	v_mul_f32_e32 v171, v171, v169
	v_rcp_f32_e32 v169, v142
	v_rcp_f32_e32 v143, v143
	v_mul_f32_e32 v170, v170, v169
	v_fma_f32 v143, v143, v137, v81
	v_med3_f32 v102, v102, s68, v188
	v_mul_f32_e32 v102, 0xbfb8aa3b, v102
	v_pk_add_f32 v[172:173], v[122:123], 1.0 op_sel_hi:[1,0]
	v_log_f32_e32 v190, v143
	v_pk_mul_f32 v[142:143], v[170:171], v[136:137]
	v_rcp_f32_e32 v170, v172
	s_nop 0
	v_fma_f32 v170, v170, v164, v82
	v_log_f32_e32 v170, v170
	v_mul_f32_e32 v169, 0x3f317218, v190
	v_max_f32_e32 v96, v96, v96
	v_med3_f32 v96, v96, s68, v188
	v_mul_f32_e32 v170, 0x3f317218, v170
	v_rcp_f32_e32 v171, v173
	v_rcp_f32_e32 v190, v172
	v_mul_f32_e32 v123, v123, v171
	v_mul_f32_e32 v122, v122, v190
	v_rcp_f32_e32 v191, v173
	s_nop 0
	v_fma_f32 v191, v191, v165, v83
	v_pk_mul_f32 v[172:173], v[122:123], v[164:165]
	v_exp_f32_e32 v190, v116
	v_log_f32_e32 v191, v191
	v_max_f32_e32 v116, v117, v117
	v_med3_f32 v116, v116, s68, v188
	v_mul_f32_e32 v116, 0xbfb8aa3b, v116
	v_mul_f32_e32 v96, 0xbfb8aa3b, v96
	v_mul_f32_e32 v122, 0x3f317218, v191
	v_exp_f32_e32 v191, v116
	v_mov_b32_e32 v171, v122
	v_lshl_add_u64 v[122:123], v[132:133], 2, s[18:19]
	global_store_dwordx4 v[122:123], v[124:127], off
	global_store_dwordx4 v[122:123], v[168:171], off offset:16
	v_max_f32_e32 v98, v98, v98
	v_cvt_pk_bf16_f32 v125, v120, v121
	v_pk_add_f32 v[168:169], v[190:191], 1.0 op_sel_hi:[1,0]
	v_cvt_pk_bf16_f32 v124, v134, v135
	v_cvt_pk_bf16_f32 v126, v142, v143
	v_max_f32_e32 v99, v99, v99
	v_med3_f32 v98, v98, s68, v188
	v_rcp_f32_e32 v116, v168
	s_nop 0
	v_fma_f32 v116, v116, v138, v76
	v_cvt_pk_bf16_f32 v127, v172, v173
	v_lshl_add_u64 v[120:121], v[132:133], 1, s[42:43]
	v_log_f32_e32 v116, v116
	global_store_dwordx4 v[120:121], v[124:127], off
	v_med3_f32 v99, v99, s68, v188
	v_mul_f32_e32 v98, 0xbfb8aa3b, v98
	v_mul_f32_e32 v99, 0xbfb8aa3b, v99
	v_exp_f32_e32 v98, v98
	v_mul_f32_e32 v116, 0x3f317218, v116
	v_rcp_f32_e32 v117, v169
	v_exp_f32_e32 v99, v99
	v_mul_f32_e32 v125, v191, v117
	v_max_f32_e32 v92, v92, v92
	v_rcp_f32_e32 v124, v169
	s_nop 0
	v_fma_f32 v124, v124, v139, v77
	v_med3_f32 v92, v92, s68, v188
	v_mul_f32_e32 v92, 0xbfb8aa3b, v92
	v_exp_f32_e32 v126, v118
	v_max_f32_e32 v118, v119, v119
	v_med3_f32 v118, v118, s68, v188
	v_mul_f32_e32 v118, 0xbfb8aa3b, v118
	v_exp_f32_e32 v127, v118
	v_log_f32_e32 v134, v124
	v_rcp_f32_e32 v117, v168
	s_nop 0
	v_mul_f32_e32 v124, v190, v117
	v_pk_mul_f32 v[124:125], v[124:125], v[138:139]
	v_pk_add_f32 v[132:133], v[126:127], 1.0 op_sel_hi:[1,0]
	v_rcp_f32_e32 v118, v132
	s_nop 0
	v_fma_f32 v118, v118, v140, v78
	v_max_f32_e32 v94, v94, v94
	v_log_f32_e32 v118, v118
	v_mul_f32_e32 v117, 0x3f317218, v134
	v_med3_f32 v94, v94, s68, v188
	v_mul_f32_e32 v94, 0xbfb8aa3b, v94
	v_mul_f32_e32 v118, 0x3f317218, v118
	v_rcp_f32_e32 v119, v133
	v_max_f32_e32 v84, v84, v84
	v_mul_f32_e32 v127, v127, v119
	v_rcp_f32_e32 v119, v132
	v_rcp_f32_e32 v133, v133
	v_mul_f32_e32 v126, v126, v119
	v_fma_f32 v133, v133, v141, v79
	v_med3_f32 v84, v84, s68, v188
	v_mul_f32_e32 v84, 0xbfb8aa3b, v84
	v_exp_f32_e32 v134, v112
	v_max_f32_e32 v112, v113, v113
	v_med3_f32 v112, v112, s68, v188
	v_mul_f32_e32 v112, 0xbfb8aa3b, v112
	v_exp_f32_e32 v135, v112
	v_pk_mul_f32 v[112:113], v[126:127], v[140:141]
	v_log_f32_e32 v133, v133
	v_max_f32_e32 v86, v86, v86
	v_pk_add_f32 v[126:127], v[134:135], 1.0 op_sel_hi:[1,0]
	v_max_f32_e32 v87, v87, v87
	v_rcp_f32_e32 v132, v126
	s_nop 0
	v_fma_f32 v132, v132, v128, v68
	v_log_f32_e32 v132, v132
	v_mul_f32_e32 v119, 0x3f317218, v133
	v_med3_f32 v86, v86, s68, v188
	v_med3_f32 v87, v87, s68, v188
	v_mul_f32_e32 v132, 0x3f317218, v132
	v_rcp_f32_e32 v133, v127
	v_mul_f32_e32 v86, 0xbfb8aa3b, v86
	v_mul_f32_e32 v135, v135, v133
	v_rcp_f32_e32 v133, v126
	v_rcp_f32_e32 v127, v127
	v_mul_f32_e32 v134, v134, v133
	v_fma_f32 v127, v127, v129, v69
	v_mul_f32_e32 v87, 0xbfb8aa3b, v87
	v_exp_f32_e32 v86, v86
	v_pk_add_f32 v[142:143], v[114:115], 1.0 op_sel_hi:[1,0]
	v_log_f32_e32 v168, v127
	v_pk_mul_f32 v[126:127], v[134:135], v[128:129]
	v_rcp_f32_e32 v134, v142
	s_nop 0
	v_fma_f32 v134, v134, v130, v70
	v_log_f32_e32 v134, v134
	v_mul_f32_e32 v133, 0x3f317218, v168
	v_exp_f32_e32 v87, v87
	v_max_f32_e32 v72, v72, v72
	v_mul_f32_e32 v134, 0x3f317218, v134
	v_rcp_f32_e32 v135, v143
	v_rcp_f32_e32 v168, v142
	v_mul_f32_e32 v115, v115, v135
	v_mul_f32_e32 v114, v114, v168
	v_rcp_f32_e32 v169, v143
	s_nop 0
	v_fma_f32 v169, v169, v131, v71
	v_pk_mul_f32 v[142:143], v[114:115], v[130:131]
	v_med3_f32 v72, v72, s68, v188
	v_log_f32_e32 v169, v169
	v_mul_f32_e32 v72, 0xbfb8aa3b, v72
	v_max_f32_e32 v74, v74, v74
	v_med3_f32 v74, v74, s68, v188
	v_mul_f32_e32 v74, 0xbfb8aa3b, v74
	v_mul_f32_e32 v114, 0x3f317218, v169
	v_mov_b32_e32 v135, v114
; DI bf16x8 pack8(const f32x4& a, const f32x4& b) { v4u w; w.x = pk2(a[0], a[1]); w.y = pk2(a[2], a[3]); w.z = pk2(b[0], b[1]); w.w = pk2(b[2], b[3]); return __builtin_bit_cast(bf16x8, w); }
;     DI void operator()(const f32x4 (&acc)[2][2][4][2], const pg8::Unit& u, int wr, int wc, int fr, int fq) const {
;     ...
;             EPI_LOOP_BEGIN
; #pragma unroll
;                 for (int bj = 0; bj < 2; ++bj) { const size_t o = (size_t)row * D + cbase + bj * 128; f32x4 lg[2], kk[2];
; #pragma unroll
;                     for (int n = 0; n < 2; ++n)
; #pragma unroll
;                         for (int e = 0; e < 4; ++e) { const float f = fminf(fmaxf(acc[ai][bj][m][n][e], -30.f), 30.f), lb = lbv[bj][n][e], ef = __expf(-f), sg = 1.f / (1.f + ef), sgn = ef / (1.f + ef);
;                             lg[n][e] = __logf(lb + (1.f - lb) * sg); kk[n][e] = (1.f - lb) * sgn; }
;                     *(f32x4*)(lf + o) = lg[0]; *(f32x4*)(lf + o + 4) = lg[1]; *(bf16x8*)(zq + (size_t)T * D + o) = pack8(kk[0], kk[1]); }
;             EPI_LOOP_END
	global_store_dwordx4 v[122:123], v[116:119], off offset:512
	global_store_dwordx4 v[122:123], v[132:135], off offset:528
	v_cvt_pk_bf16_f32 v115, v112, v113
	v_exp_f32_e32 v118, v108
	v_max_f32_e32 v108, v109, v109
	v_med3_f32 v108, v108, s68, v188
	v_mul_f32_e32 v108, 0xbfb8aa3b, v108
	v_exp_f32_e32 v119, v108
	v_cvt_pk_bf16_f32 v114, v124, v125
	v_cvt_pk_bf16_f32 v116, v126, v127
	v_cvt_pk_bf16_f32 v117, v142, v143
	v_pk_add_f32 v[122:123], v[118:119], 1.0 op_sel_hi:[1,0]
	global_store_dwordx4 v[120:121], v[114:117], off offset:256
	v_add_u32_e32 v108, s45, v179
	v_max_f32_e32 v64, v64, v64
	v_med3_f32 v64, v64, s68, v188
	v_rcp_f32_e32 v109, v122
	s_nop 0
	v_fma_f32 v109, v109, v166, v88
	v_mul_f32_e32 v64, 0xbfb8aa3b, v64
	v_max_f32_e32 v66, v66, v66
	v_log_f32_e32 v114, v109
	v_ashrrev_i32_e32 v109, 31, v108
	v_lshlrev_b64 v[108:109], 11, v[108:109]
	v_lshl_add_u64 v[112:113], v[108:109], 0, v[160:161]
	v_max_f32_e32 v67, v67, v67
	v_med3_f32 v66, v66, s68, v188
	v_mul_f32_e32 v108, 0x3f317218, v114
	v_rcp_f32_e32 v109, v123
	s_nop 0
	v_mul_f32_e32 v115, v119, v109
	v_med3_f32 v67, v67, s68, v188
	v_mul_f32_e32 v66, 0xbfb8aa3b, v66
	v_rcp_f32_e32 v114, v123
	s_nop 0
	v_fma_f32 v114, v114, v167, v89
	v_mul_f32_e32 v67, 0xbfb8aa3b, v67
	v_exp_f32_e32 v66, v66
	v_exp_f32_e32 v116, v110
	v_max_f32_e32 v110, v111, v111
	v_med3_f32 v110, v110, s68, v188
	v_mul_f32_e32 v110, 0xbfb8aa3b, v110
	v_exp_f32_e32 v117, v110
	v_log_f32_e32 v120, v114
	v_rcp_f32_e32 v109, v122
	s_nop 0
	v_mul_f32_e32 v114, v118, v109
	v_pk_mul_f32 v[114:115], v[114:115], v[166:167]
	v_pk_add_f32 v[118:119], v[116:117], 1.0 op_sel_hi:[1,0]
	v_rcp_f32_e32 v110, v118
	s_nop 0
	v_fma_f32 v110, v110, v162, v90
	v_exp_f32_e32 v67, v67
	v_log_f32_e32 v110, v110
	v_mul_f32_e32 v109, 0x3f317218, v120
	v_max_f32_e32 v60, v60, v60
	v_med3_f32 v60, v60, s68, v188
	v_mul_f32_e32 v110, 0x3f317218, v110
	v_rcp_f32_e32 v111, v119
	v_mul_f32_e32 v60, 0xbfb8aa3b, v60
	v_mul_f32_e32 v117, v117, v111
	v_rcp_f32_e32 v111, v118
	v_rcp_f32_e32 v119, v119
	v_mul_f32_e32 v116, v116, v111
	v_fma_f32 v119, v119, v163, v91
	v_max_f32_e32 v62, v62, v62
	v_med3_f32 v62, v62, s68, v188
	v_exp_f32_e32 v120, v104
	v_max_f32_e32 v104, v105, v105
	v_med3_f32 v104, v104, s68, v188
	v_mul_f32_e32 v104, 0xbfb8aa3b, v104
	v_exp_f32_e32 v121, v104
	v_log_f32_e32 v122, v119
	v_pk_mul_f32 v[104:105], v[116:117], v[162:163]
	v_mul_f32_e32 v62, 0xbfb8aa3b, v62
	v_pk_add_f32 v[118:119], v[120:121], 1.0 op_sel_hi:[1,0]
	v_rcp_f32_e32 v116, v118
	s_nop 0
	v_fma_f32 v116, v116, v136, v80
	v_max_f32_e32 v56, v56, v56
	v_log_f32_e32 v116, v116
	v_mul_f32_e32 v111, 0x3f317218, v122
	v_med3_f32 v56, v56, s68, v188
	v_mul_f32_e32 v56, 0xbfb8aa3b, v56
	v_mul_f32_e32 v116, 0x3f317218, v116
	v_rcp_f32_e32 v117, v119
	v_max_f32_e32 v58, v58, v58
	v_mul_f32_e32 v121, v121, v117
	v_rcp_f32_e32 v117, v118
	v_rcp_f32_e32 v119, v119
	v_mul_f32_e32 v120, v120, v117
	v_fma_f32 v119, v119, v137, v81
	v_pk_mul_f32 v[120:121], v[120:121], v[136:137]
	v_max_f32_e32 v59, v59, v59
	v_pk_add_f32 v[122:123], v[106:107], 1.0 op_sel_hi:[1,0]
	v_log_f32_e32 v119, v119
	s_nop 0
	v_rcp_f32_e32 v118, v122
	s_nop 0
	v_fma_f32 v118, v118, v164, v82
	v_log_f32_e32 v118, v118
	v_mul_f32_e32 v117, 0x3f317218, v119
	v_med3_f32 v58, v58, s68, v188
	v_med3_f32 v59, v59, s68, v188
	v_mul_f32_e32 v118, 0x3f317218, v118
	v_rcp_f32_e32 v119, v123
	v_rcp_f32_e32 v124, v122
	v_mul_f32_e32 v107, v107, v119
	v_mul_f32_e32 v106, v106, v124
	v_rcp_f32_e32 v125, v123
	s_nop 0
	v_fma_f32 v125, v125, v165, v83
	v_pk_mul_f32 v[122:123], v[106:107], v[164:165]
	v_exp_f32_e32 v124, v100
	v_log_f32_e32 v125, v125
	v_max_f32_e32 v100, v101, v101
	v_med3_f32 v100, v100, s68, v188
	v_mul_f32_e32 v100, 0xbfb8aa3b, v100
	v_mul_f32_e32 v58, 0xbfb8aa3b, v58
	v_mul_f32_e32 v106, 0x3f317218, v125
	v_exp_f32_e32 v125, v100
	v_mov_b32_e32 v119, v106
	v_lshl_add_u64 v[106:107], v[112:113], 2, s[18:19]
	global_store_dwordx4 v[106:107], v[108:111], off
	global_store_dwordx4 v[106:107], v[116:119], off offset:16
	v_mul_f32_e32 v59, 0xbfb8aa3b, v59
	v_cvt_pk_bf16_f32 v109, v104, v105
	v_pk_add_f32 v[116:117], v[124:125], 1.0 op_sel_hi:[1,0]
	v_cvt_pk_bf16_f32 v108, v114, v115
	v_cvt_pk_bf16_f32 v110, v120, v121
	v_exp_f32_e32 v58, v58
	v_exp_f32_e32 v59, v59
	v_rcp_f32_e32 v100, v116
	s_nop 0
	v_fma_f32 v100, v100, v138, v76
	v_cvt_pk_bf16_f32 v111, v122, v123
	v_lshl_add_u64 v[104:105], v[112:113], 1, s[42:43]
	v_log_f32_e32 v100, v100
	global_store_dwordx4 v[104:105], v[108:111], off
	v_max_f32_e32 v52, v52, v52
	v_med3_f32 v52, v52, s68, v188
	v_mul_f32_e32 v52, 0xbfb8aa3b, v52
	v_max_f32_e32 v54, v54, v54
	v_mul_f32_e32 v100, 0x3f317218, v100
	v_rcp_f32_e32 v101, v117
	s_nop 0
	v_mul_f32_e32 v109, v125, v101
	v_med3_f32 v54, v54, s68, v188
	v_mul_f32_e32 v54, 0xbfb8aa3b, v54
	v_rcp_f32_e32 v108, v117
	s_nop 0
	v_fma_f32 v108, v108, v139, v77
	v_max_f32_e32 v48, v48, v48
	v_med3_f32 v48, v48, s68, v188
	v_exp_f32_e32 v110, v102
	v_max_f32_e32 v102, v103, v103
	v_med3_f32 v102, v102, s68, v188
	v_mul_f32_e32 v102, 0xbfb8aa3b, v102
	v_exp_f32_e32 v111, v102
	v_log_f32_e32 v114, v108
	v_rcp_f32_e32 v101, v116
	s_nop 0
	v_mul_f32_e32 v108, v124, v101
	v_pk_mul_f32 v[108:109], v[108:109], v[138:139]
	v_pk_add_f32 v[112:113], v[110:111], 1.0 op_sel_hi:[1,0]
	v_rcp_f32_e32 v102, v112
	s_nop 0
	v_fma_f32 v102, v102, v140, v78
	v_mul_f32_e32 v48, 0xbfb8aa3b, v48
	v_log_f32_e32 v102, v102
	v_mul_f32_e32 v101, 0x3f317218, v114
	v_max_f32_e32 v50, v50, v50
	v_max_f32_e32 v51, v51, v51
	v_mul_f32_e32 v102, 0x3f317218, v102
	v_rcp_f32_e32 v103, v113
	s_nop 0
	v_mul_f32_e32 v111, v111, v103
; DI bf16x8 pack8(const f32x4& a, const f32x4& b) { v4u w; w.x = pk2(a[0], a[1]); w.y = pk2(a[2], a[3]); w.z = pk2(b[0], b[1]); w.w = pk2(b[2], b[3]); return __builtin_bit_cast(bf16x8, w); }
;     DI void operator()(const f32x4 (&acc)[2][2][4][2], const pg8::Unit& u, int wr, int wc, int fr, int fq) const {
;     ...
;             EPI_LOOP_BEGIN
; #pragma unroll
;                 for (int bj = 0; bj < 2; ++bj) { const size_t o = (size_t)row * D + cbase + bj * 128; f32x4 lg[2], kk[2];
; #pragma unroll
;                     for (int n = 0; n < 2; ++n)
; #pragma unroll
;                         for (int e = 0; e < 4; ++e) { const float f = fminf(fmaxf(acc[ai][bj][m][n][e], -30.f), 30.f), lb = lbv[bj][n][e], ef = __expf(-f), sg = 1.f / (1.f + ef), sgn = ef / (1.f + ef);
;                             lg[n][e] = __logf(lb + (1.f - lb) * sg); kk[n][e] = (1.f - lb) * sgn; }
;                     *(f32x4*)(lf + o) = lg[0]; *(f32x4*)(lf + o + 4) = lg[1]; *(bf16x8*)(zq + (size_t)T * D + o) = pack8(kk[0], kk[1]); }
;             EPI_LOOP_END
	v_med3_f32 v50, v50, s68, v188
	v_rcp_f32_e32 v103, v112
	v_rcp_f32_e32 v113, v113
	v_mul_f32_e32 v110, v110, v103
	v_fma_f32 v113, v113, v141, v79
	v_med3_f32 v51, v51, s68, v188
	v_mul_f32_e32 v50, 0xbfb8aa3b, v50
	v_exp_f32_e32 v114, v96
	v_max_f32_e32 v96, v97, v97
	v_med3_f32 v96, v96, s68, v188
	v_mul_f32_e32 v96, 0xbfb8aa3b, v96
	v_exp_f32_e32 v115, v96
	v_log_f32_e32 v116, v113
	v_pk_mul_f32 v[96:97], v[110:111], v[140:141]
	v_mul_f32_e32 v51, 0xbfb8aa3b, v51
	v_pk_add_f32 v[112:113], v[114:115], 1.0 op_sel_hi:[1,0]
	v_rcp_f32_e32 v110, v112
	s_nop 0
	v_fma_f32 v110, v110, v128, v68
	v_exp_f32_e32 v50, v50
	v_log_f32_e32 v110, v110
	v_mul_f32_e32 v103, 0x3f317218, v116
	v_exp_f32_e32 v51, v51
	v_max_f32_e32 v44, v44, v44
	v_mul_f32_e32 v110, 0x3f317218, v110
	v_rcp_f32_e32 v111, v113
	s_nop 0
	v_mul_f32_e32 v115, v115, v111
	v_med3_f32 v44, v44, s68, v188
	v_rcp_f32_e32 v111, v112
	v_rcp_f32_e32 v113, v113
	v_mul_f32_e32 v114, v114, v111
	v_fma_f32 v113, v113, v129, v69
	v_pk_mul_f32 v[114:115], v[114:115], v[128:129]
	v_mul_f32_e32 v44, 0xbfb8aa3b, v44
	v_pk_add_f32 v[116:117], v[98:99], 1.0 op_sel_hi:[1,0]
	v_log_f32_e32 v113, v113
	s_nop 0
	v_rcp_f32_e32 v112, v116
	s_nop 0
	v_fma_f32 v112, v112, v130, v70
	v_log_f32_e32 v112, v112
	v_mul_f32_e32 v111, 0x3f317218, v113
	v_max_f32_e32 v46, v46, v46
	v_med3_f32 v46, v46, s68, v188
	v_mul_f32_e32 v112, 0x3f317218, v112
	v_rcp_f32_e32 v113, v117
	v_rcp_f32_e32 v118, v116
	v_mul_f32_e32 v99, v99, v113
	v_mul_f32_e32 v98, v98, v118
	v_rcp_f32_e32 v119, v117
	s_nop 0
	v_fma_f32 v119, v119, v131, v71
	v_pk_mul_f32 v[116:117], v[98:99], v[130:131]
	v_mul_f32_e32 v46, 0xbfb8aa3b, v46
	v_log_f32_e32 v119, v119
	v_max_f32_e32 v40, v40, v40
	v_med3_f32 v40, v40, s68, v188
	v_mul_f32_e32 v40, 0xbfb8aa3b, v40
	v_max_f32_e32 v42, v42, v42
	v_mul_f32_e32 v98, 0x3f317218, v119
	v_mov_b32_e32 v113, v98
	global_store_dwordx4 v[106:107], v[100:103], off offset:512
	global_store_dwordx4 v[106:107], v[110:113], off offset:528
	v_cvt_pk_bf16_f32 v99, v96, v97
	v_exp_f32_e32 v102, v92
	v_max_f32_e32 v92, v93, v93
	v_med3_f32 v92, v92, s68, v188
	v_mul_f32_e32 v92, 0xbfb8aa3b, v92
	v_exp_f32_e32 v103, v92
	v_cvt_pk_bf16_f32 v98, v108, v109
	v_cvt_pk_bf16_f32 v100, v114, v115
	v_cvt_pk_bf16_f32 v101, v116, v117
	v_pk_add_f32 v[106:107], v[102:103], 1.0 op_sel_hi:[1,0]
	global_store_dwordx4 v[104:105], v[98:101], off offset:256
	v_add_u32_e32 v92, s45, v180
	v_max_f32_e32 v43, v43, v43
	v_med3_f32 v42, v42, s68, v188
	v_rcp_f32_e32 v93, v106
	s_nop 0
	v_fma_f32 v93, v93, v166, v88
	v_med3_f32 v43, v43, s68, v188
	v_mul_f32_e32 v42, 0xbfb8aa3b, v42
	v_log_f32_e32 v98, v93
	v_ashrrev_i32_e32 v93, 31, v92
	v_lshlrev_b64 v[92:93], 11, v[92:93]
	v_lshl_add_u64 v[96:97], v[92:93], 0, v[160:161]
	v_mul_f32_e32 v43, 0xbfb8aa3b, v43
	v_exp_f32_e32 v42, v42
	v_mul_f32_e32 v92, 0x3f317218, v98
	v_rcp_f32_e32 v93, v107
	v_exp_f32_e32 v43, v43
	v_mul_f32_e32 v99, v103, v93
	v_max_f32_e32 v36, v36, v36
	v_rcp_f32_e32 v98, v107
	s_nop 0
	v_fma_f32 v98, v98, v167, v89
	v_med3_f32 v36, v36, s68, v188
	v_mul_f32_e32 v36, 0xbfb8aa3b, v36
	v_exp_f32_e32 v100, v94
	v_max_f32_e32 v94, v95, v95
	v_med3_f32 v94, v94, s68, v188
	v_mul_f32_e32 v94, 0xbfb8aa3b, v94
	v_exp_f32_e32 v101, v94
	v_log_f32_e32 v104, v98
	v_rcp_f32_e32 v93, v106
	s_nop 0
	v_mul_f32_e32 v98, v102, v93
	v_pk_mul_f32 v[98:99], v[98:99], v[166:167]
	v_pk_add_f32 v[102:103], v[100:101], 1.0 op_sel_hi:[1,0]
	v_rcp_f32_e32 v94, v102
	s_nop 0
	v_fma_f32 v94, v94, v162, v90
	v_max_f32_e32 v38, v38, v38
	v_log_f32_e32 v94, v94
	v_mul_f32_e32 v93, 0x3f317218, v104
	v_med3_f32 v38, v38, s68, v188
	v_mul_f32_e32 v38, 0xbfb8aa3b, v38
	v_mul_f32_e32 v94, 0x3f317218, v94
	v_rcp_f32_e32 v95, v103
	v_max_f32_e32 v32, v32, v32
	v_mul_f32_e32 v101, v101, v95
	v_rcp_f32_e32 v95, v102
	v_rcp_f32_e32 v103, v103
	v_mul_f32_e32 v100, v100, v95
	v_fma_f32 v103, v103, v163, v91
	v_med3_f32 v32, v32, s68, v188
	v_mul_f32_e32 v32, 0xbfb8aa3b, v32
	v_exp_f32_e32 v104, v84
	v_max_f32_e32 v84, v85, v85
	v_med3_f32 v84, v84, s68, v188
	v_mul_f32_e32 v84, 0xbfb8aa3b, v84
	v_exp_f32_e32 v105, v84
	v_log_f32_e32 v106, v103
	v_pk_mul_f32 v[84:85], v[100:101], v[162:163]
	v_max_f32_e32 v34, v34, v34
	v_pk_add_f32 v[102:103], v[104:105], 1.0 op_sel_hi:[1,0]
	v_rcp_f32_e32 v100, v102
	s_nop 0
	v_fma_f32 v100, v100, v136, v80
	v_max_f32_e32 v35, v35, v35
	v_log_f32_e32 v100, v100
	v_mul_f32_e32 v95, 0x3f317218, v106
	v_med3_f32 v34, v34, s68, v188
	v_med3_f32 v35, v35, s68, v188
	v_mul_f32_e32 v100, 0x3f317218, v100
	v_rcp_f32_e32 v101, v103
	v_mul_f32_e32 v34, 0xbfb8aa3b, v34
	v_mul_f32_e32 v105, v105, v101
	v_rcp_f32_e32 v101, v102
	v_rcp_f32_e32 v103, v103
	v_mul_f32_e32 v104, v104, v101
	v_fma_f32 v103, v103, v137, v81
	v_pk_mul_f32 v[104:105], v[104:105], v[136:137]
	v_mul_f32_e32 v35, 0xbfb8aa3b, v35
	v_pk_add_f32 v[106:107], v[86:87], 1.0 op_sel_hi:[1,0]
	v_log_f32_e32 v103, v103
	s_nop 0
	v_rcp_f32_e32 v102, v106
	s_nop 0
	v_fma_f32 v102, v102, v164, v82
	v_log_f32_e32 v102, v102
	v_mul_f32_e32 v101, 0x3f317218, v103
	v_exp_f32_e32 v34, v34
	v_exp_f32_e32 v35, v35
	v_mul_f32_e32 v102, 0x3f317218, v102
	v_rcp_f32_e32 v103, v107
	v_rcp_f32_e32 v108, v106
	v_mul_f32_e32 v87, v87, v103
	v_mul_f32_e32 v86, v86, v108
	v_rcp_f32_e32 v109, v107
	s_nop 0
	v_fma_f32 v109, v109, v165, v83
	v_pk_mul_f32 v[106:107], v[86:87], v[164:165]
	v_exp_f32_e32 v108, v72
	v_log_f32_e32 v109, v109
	v_max_f32_e32 v72, v73, v73
	v_med3_f32 v72, v72, s68, v188
	v_mul_f32_e32 v72, 0xbfb8aa3b, v72
	v_max_f32_e32 v28, v28, v28
	v_mul_f32_e32 v86, 0x3f317218, v109
	v_exp_f32_e32 v109, v72
	v_mov_b32_e32 v103, v86
; DI bf16x8 pack8(const f32x4& a, const f32x4& b) { v4u w; w.x = pk2(a[0], a[1]); w.y = pk2(a[2], a[3]); w.z = pk2(b[0], b[1]); w.w = pk2(b[2], b[3]); return __builtin_bit_cast(bf16x8, w); }
;     DI void operator()(const f32x4 (&acc)[2][2][4][2], const pg8::Unit& u, int wr, int wc, int fr, int fq) const {
;     ...
;             EPI_LOOP_BEGIN
; #pragma unroll
;                 for (int bj = 0; bj < 2; ++bj) { const size_t o = (size_t)row * D + cbase + bj * 128; f32x4 lg[2], kk[2];
; #pragma unroll
;                     for (int n = 0; n < 2; ++n)
; #pragma unroll
;                         for (int e = 0; e < 4; ++e) { const float f = fminf(fmaxf(acc[ai][bj][m][n][e], -30.f), 30.f), lb = lbv[bj][n][e], ef = __expf(-f), sg = 1.f / (1.f + ef), sgn = ef / (1.f + ef);
;                             lg[n][e] = __logf(lb + (1.f - lb) * sg); kk[n][e] = (1.f - lb) * sgn; }
;                     *(f32x4*)(lf + o) = lg[0]; *(f32x4*)(lf + o + 4) = lg[1]; *(bf16x8*)(zq + (size_t)T * D + o) = pack8(kk[0], kk[1]); }
;             EPI_LOOP_END
	v_lshl_add_u64 v[86:87], v[96:97], 2, s[18:19]
	global_store_dwordx4 v[86:87], v[92:95], off
	global_store_dwordx4 v[86:87], v[100:103], off offset:16
	v_med3_f32 v28, v28, s68, v188
	v_cvt_pk_bf16_f32 v93, v84, v85
	v_pk_add_f32 v[100:101], v[108:109], 1.0 op_sel_hi:[1,0]
	v_cvt_pk_bf16_f32 v92, v98, v99
	v_cvt_pk_bf16_f32 v94, v104, v105
	v_mul_f32_e32 v28, 0xbfb8aa3b, v28
	v_max_f32_e32 v30, v30, v30
	v_rcp_f32_e32 v72, v100
	s_nop 0
	v_fma_f32 v72, v72, v138, v76
	v_cvt_pk_bf16_f32 v95, v106, v107
	v_lshl_add_u64 v[84:85], v[96:97], 1, s[42:43]
	v_log_f32_e32 v72, v72
	global_store_dwordx4 v[84:85], v[92:95], off
	v_med3_f32 v30, v30, s68, v188
	v_mul_f32_e32 v30, 0xbfb8aa3b, v30
	v_max_f32_e32 v24, v24, v24
	v_med3_f32 v24, v24, s68, v188
	v_mul_f32_e32 v72, 0x3f317218, v72
	v_rcp_f32_e32 v73, v101
	v_mul_f32_e32 v24, 0xbfb8aa3b, v24
	v_mul_f32_e32 v93, v109, v73
	v_max_f32_e32 v26, v26, v26
	v_rcp_f32_e32 v92, v101
	s_nop 0
	v_fma_f32 v92, v92, v139, v77
	v_max_f32_e32 v27, v27, v27
	v_med3_f32 v26, v26, s68, v188
	v_exp_f32_e32 v94, v74
	v_max_f32_e32 v74, v75, v75
	v_med3_f32 v74, v74, s68, v188
	v_mul_f32_e32 v74, 0xbfb8aa3b, v74
	v_exp_f32_e32 v95, v74
	v_log_f32_e32 v98, v92
	v_rcp_f32_e32 v73, v100
	s_nop 0
	v_mul_f32_e32 v92, v108, v73
	v_pk_mul_f32 v[92:93], v[92:93], v[138:139]
	v_pk_add_f32 v[96:97], v[94:95], 1.0 op_sel_hi:[1,0]
	v_rcp_f32_e32 v74, v96
	s_nop 0
	v_fma_f32 v74, v74, v140, v78
	v_med3_f32 v27, v27, s68, v188
	v_log_f32_e32 v74, v74
	v_mul_f32_e32 v73, 0x3f317218, v98
	v_mul_f32_e32 v26, 0xbfb8aa3b, v26
	v_mul_f32_e32 v27, 0xbfb8aa3b, v27
	v_mul_f32_e32 v74, 0x3f317218, v74
	v_rcp_f32_e32 v75, v97
	v_exp_f32_e32 v26, v26
	v_mul_f32_e32 v95, v95, v75
	v_rcp_f32_e32 v75, v96
	v_rcp_f32_e32 v97, v97
	v_mul_f32_e32 v94, v94, v75
	v_fma_f32 v97, v97, v141, v79
	v_exp_f32_e32 v27, v27
	v_max_f32_e32 v20, v20, v20
	v_exp_f32_e32 v98, v64
	v_max_f32_e32 v64, v65, v65
	v_med3_f32 v64, v64, s68, v188
	v_mul_f32_e32 v64, 0xbfb8aa3b, v64
	v_exp_f32_e32 v99, v64
	v_log_f32_e32 v100, v97
	v_pk_mul_f32 v[64:65], v[94:95], v[140:141]
	v_med3_f32 v20, v20, s68, v188
	v_pk_add_f32 v[96:97], v[98:99], 1.0 op_sel_hi:[1,0]
	v_rcp_f32_e32 v94, v96
	s_nop 0
	v_fma_f32 v94, v94, v128, v68
	v_mul_f32_e32 v20, 0xbfb8aa3b, v20
	v_log_f32_e32 v94, v94
	v_mul_f32_e32 v75, 0x3f317218, v100
	v_max_f32_e32 v22, v22, v22
	v_med3_f32 v22, v22, s68, v188
	v_mul_f32_e32 v94, 0x3f317218, v94
	v_rcp_f32_e32 v95, v97
	v_mul_f32_e32 v22, 0xbfb8aa3b, v22
	v_mul_f32_e32 v99, v99, v95
	v_rcp_f32_e32 v95, v96
	v_rcp_f32_e32 v97, v97
	v_mul_f32_e32 v98, v98, v95
	v_fma_f32 v97, v97, v129, v69
	v_pk_mul_f32 v[98:99], v[98:99], v[128:129]
	v_max_f32_e32 v16, v16, v16
	v_pk_add_f32 v[100:101], v[66:67], 1.0 op_sel_hi:[1,0]
	v_log_f32_e32 v97, v97
	s_nop 0
	v_rcp_f32_e32 v96, v100
	s_nop 0
	v_fma_f32 v96, v96, v130, v70
	v_log_f32_e32 v96, v96
	v_mul_f32_e32 v95, 0x3f317218, v97
	v_med3_f32 v16, v16, s68, v188
	v_mul_f32_e32 v16, 0xbfb8aa3b, v16
	v_mul_f32_e32 v96, 0x3f317218, v96
	v_rcp_f32_e32 v97, v101
	v_rcp_f32_e32 v102, v100
	v_mul_f32_e32 v67, v67, v97
	v_mul_f32_e32 v66, v66, v102
	v_rcp_f32_e32 v103, v101
	s_nop 0
	v_fma_f32 v103, v103, v131, v71
	v_pk_mul_f32 v[66:67], v[66:67], v[130:131]
	v_max_f32_e32 v18, v18, v18
	v_log_f32_e32 v103, v103
	v_max_f32_e32 v19, v19, v19
	v_med3_f32 v18, v18, s68, v188
	v_med3_f32 v19, v19, s68, v188
	v_mul_f32_e32 v18, 0xbfb8aa3b, v18
	v_mul_f32_e32 v97, 0x3f317218, v103
	global_store_dwordx4 v[86:87], v[72:75], off offset:512
	global_store_dwordx4 v[86:87], v[94:97], off offset:528
	v_exp_f32_e32 v86, v60
	v_max_f32_e32 v60, v61, v61
	v_med3_f32 v60, v60, s68, v188
	v_mul_f32_e32 v60, 0xbfb8aa3b, v60
	v_exp_f32_e32 v87, v60
	v_cvt_pk_bf16_f32 v72, v92, v93
	v_cvt_pk_bf16_f32 v73, v64, v65
	v_cvt_pk_bf16_f32 v75, v66, v67
	v_pk_add_f32 v[92:93], v[86:87], 1.0 op_sel_hi:[1,0]
	v_add_u32_e32 v60, s45, v181
	v_cvt_pk_bf16_f32 v74, v98, v99
	global_store_dwordx4 v[84:85], v[72:75], off offset:256
	v_mul_f32_e32 v19, 0xbfb8aa3b, v19
	v_rcp_f32_e32 v61, v92
	s_nop 0
	v_fma_f32 v61, v61, v166, v88
	v_exp_f32_e32 v18, v18
	v_exp_f32_e32 v19, v19
	v_log_f32_e32 v66, v61
	v_ashrrev_i32_e32 v61, 31, v60
	v_lshlrev_b64 v[60:61], 11, v[60:61]
	v_lshl_add_u64 v[64:65], v[60:61], 0, v[160:161]
	v_max_f32_e32 v12, v12, v12
	v_med3_f32 v12, v12, s68, v188
	v_mul_f32_e32 v60, 0x3f317218, v66
	v_rcp_f32_e32 v61, v93
	v_mul_f32_e32 v12, 0xbfb8aa3b, v12
	v_mul_f32_e32 v67, v87, v61
	v_max_f32_e32 v14, v14, v14
	v_rcp_f32_e32 v66, v93
	s_nop 0
	v_fma_f32 v66, v66, v167, v89
	v_med3_f32 v14, v14, s68, v188
	v_mul_f32_e32 v14, 0xbfb8aa3b, v14
	v_exp_f32_e32 v72, v62
	v_max_f32_e32 v62, v63, v63
	v_med3_f32 v62, v62, s68, v188
	v_mul_f32_e32 v62, 0xbfb8aa3b, v62
	v_exp_f32_e32 v73, v62
	v_log_f32_e32 v84, v66
	v_rcp_f32_e32 v61, v92
	s_nop 0
	v_mul_f32_e32 v66, v86, v61
	v_pk_mul_f32 v[66:67], v[66:67], v[166:167]
	v_pk_add_f32 v[74:75], v[72:73], 1.0 op_sel_hi:[1,0]
	v_rcp_f32_e32 v62, v74
	s_nop 0
	v_fma_f32 v62, v62, v162, v90
	v_max_f32_e32 v8, v8, v8
	v_log_f32_e32 v62, v62
	v_mul_f32_e32 v61, 0x3f317218, v84
	v_max_f32_e32 v9, v9, v9
	v_med3_f32 v8, v8, s68, v188
	v_mul_f32_e32 v62, 0x3f317218, v62
	v_rcp_f32_e32 v63, v75
	s_nop 0
	v_mul_f32_e32 v73, v73, v63
	v_med3_f32 v9, v9, s68, v188
	v_rcp_f32_e32 v63, v74
	v_rcp_f32_e32 v75, v75
	v_mul_f32_e32 v72, v72, v63
	v_fma_f32 v75, v75, v163, v91
	v_mul_f32_e32 v8, 0xbfb8aa3b, v8
	v_mul_f32_e32 v9, 0xbfb8aa3b, v9
	v_exp_f32_e32 v84, v56
	v_max_f32_e32 v56, v57, v57
	v_med3_f32 v56, v56, s68, v188
	v_mul_f32_e32 v56, 0xbfb8aa3b, v56
	v_exp_f32_e32 v85, v56
	v_log_f32_e32 v86, v75
; DI bf16x8 pack8(const f32x4& a, const f32x4& b) { v4u w; w.x = pk2(a[0], a[1]); w.y = pk2(a[2], a[3]); w.z = pk2(b[0], b[1]); w.w = pk2(b[2], b[3]); return __builtin_bit_cast(bf16x8, w); }
;     DI void operator()(const f32x4 (&acc)[2][2][4][2], const pg8::Unit& u, int wr, int wc, int fr, int fq) const {
;     ...
;             EPI_LOOP_BEGIN
; #pragma unroll
;                 for (int bj = 0; bj < 2; ++bj) { const size_t o = (size_t)row * D + cbase + bj * 128; f32x4 lg[2], kk[2];
; #pragma unroll
;                     for (int n = 0; n < 2; ++n)
; #pragma unroll
;                         for (int e = 0; e < 4; ++e) { const float f = fminf(fmaxf(acc[ai][bj][m][n][e], -30.f), 30.f), lb = lbv[bj][n][e], ef = __expf(-f), sg = 1.f / (1.f + ef), sgn = ef / (1.f + ef);
;                             lg[n][e] = __logf(lb + (1.f - lb) * sg); kk[n][e] = (1.f - lb) * sgn; }
;                     *(f32x4*)(lf + o) = lg[0]; *(f32x4*)(lf + o + 4) = lg[1]; *(bf16x8*)(zq + (size_t)T * D + o) = pack8(kk[0], kk[1]); }
;             EPI_LOOP_END
	v_pk_mul_f32 v[56:57], v[72:73], v[162:163]
	v_exp_f32_e32 v8, v8
	v_pk_add_f32 v[74:75], v[84:85], 1.0 op_sel_hi:[1,0]
	v_rcp_f32_e32 v72, v74
	s_nop 0
	v_fma_f32 v72, v72, v136, v80
	v_exp_f32_e32 v9, v9
	v_log_f32_e32 v72, v72
	v_mul_f32_e32 v63, 0x3f317218, v86
	v_max_f32_e32 v10, v10, v10
	v_max_f32_e32 v11, v11, v11
	v_mul_f32_e32 v72, 0x3f317218, v72
	v_rcp_f32_e32 v73, v75
	s_nop 0
	v_mul_f32_e32 v85, v85, v73
	v_med3_f32 v10, v10, s68, v188
	v_rcp_f32_e32 v73, v74
	v_rcp_f32_e32 v75, v75
	v_mul_f32_e32 v84, v84, v73
	v_fma_f32 v75, v75, v137, v81
	v_pk_mul_f32 v[84:85], v[84:85], v[136:137]
	v_med3_f32 v11, v11, s68, v188
	v_pk_add_f32 v[86:87], v[58:59], 1.0 op_sel_hi:[1,0]
	v_log_f32_e32 v75, v75
	s_nop 0
	v_rcp_f32_e32 v74, v86
	s_nop 0
	v_fma_f32 v74, v74, v164, v82
	v_log_f32_e32 v74, v74
	v_mul_f32_e32 v73, 0x3f317218, v75
	v_mul_f32_e32 v10, 0xbfb8aa3b, v10
	v_mul_f32_e32 v11, 0xbfb8aa3b, v11
	v_mul_f32_e32 v74, 0x3f317218, v74
	v_rcp_f32_e32 v75, v87
	v_rcp_f32_e32 v92, v86
	v_mul_f32_e32 v59, v59, v75
	v_mul_f32_e32 v58, v58, v92
	v_rcp_f32_e32 v93, v87
	s_nop 0
	v_fma_f32 v93, v93, v165, v83
	v_pk_mul_f32 v[86:87], v[58:59], v[164:165]
	v_exp_f32_e32 v92, v52
	v_log_f32_e32 v93, v93
	v_max_f32_e32 v52, v53, v53
	v_med3_f32 v52, v52, s68, v188
	v_mul_f32_e32 v52, 0xbfb8aa3b, v52
	v_exp_f32_e32 v10, v10
	v_mul_f32_e32 v58, 0x3f317218, v93
	v_exp_f32_e32 v93, v52
	v_mov_b32_e32 v75, v58
	v_lshl_add_u64 v[58:59], v[64:65], 2, s[18:19]
	global_store_dwordx4 v[58:59], v[60:63], off
	global_store_dwordx4 v[58:59], v[72:75], off offset:16
	v_exp_f32_e32 v11, v11
	v_cvt_pk_bf16_f32 v61, v56, v57
	v_pk_add_f32 v[72:73], v[92:93], 1.0 op_sel_hi:[1,0]
	v_cvt_pk_bf16_f32 v60, v66, v67
	v_cvt_pk_bf16_f32 v62, v84, v85
	v_max_f32_e32 v4, v4, v4
	v_med3_f32 v4, v4, s68, v188
	v_rcp_f32_e32 v52, v72
	s_nop 0
	v_fma_f32 v52, v52, v138, v76
	v_cvt_pk_bf16_f32 v63, v86, v87
	v_lshl_add_u64 v[56:57], v[64:65], 1, s[42:43]
	v_log_f32_e32 v52, v52
	global_store_dwordx4 v[56:57], v[60:63], off
	v_mul_f32_e32 v4, 0xbfb8aa3b, v4
	v_max_f32_e32 v6, v6, v6
	v_med3_f32 v6, v6, s68, v188
	v_mul_f32_e32 v6, 0xbfb8aa3b, v6
	v_mul_f32_e32 v52, 0x3f317218, v52
	v_rcp_f32_e32 v53, v73
	v_max_f32_e32 v0, v0, v0
	v_mul_f32_e32 v61, v93, v53
	v_med3_f32 v0, v0, s68, v188
	v_rcp_f32_e32 v60, v73
	s_nop 0
	v_fma_f32 v60, v60, v139, v77
	v_mul_f32_e32 v0, 0xbfb8aa3b, v0
	v_max_f32_e32 v2, v2, v2
	v_exp_f32_e32 v62, v54
	v_max_f32_e32 v54, v55, v55
	v_med3_f32 v54, v54, s68, v188
	v_mul_f32_e32 v54, 0xbfb8aa3b, v54
	v_exp_f32_e32 v63, v54
	v_log_f32_e32 v66, v60
	v_rcp_f32_e32 v53, v72
	s_nop 0
	v_mul_f32_e32 v60, v92, v53
	v_pk_mul_f32 v[60:61], v[60:61], v[138:139]
	v_pk_add_f32 v[64:65], v[62:63], 1.0 op_sel_hi:[1,0]
	v_rcp_f32_e32 v54, v64
	s_nop 0
	v_fma_f32 v54, v54, v140, v78
	v_med3_f32 v2, v2, s68, v188
	v_log_f32_e32 v54, v54
	v_mul_f32_e32 v53, 0x3f317218, v66
	v_mul_f32_e32 v2, 0xbfb8aa3b, v2
	s_nop 0
	v_mul_f32_e32 v54, 0x3f317218, v54
	v_rcp_f32_e32 v55, v65
	s_nop 0
	v_mul_f32_e32 v63, v63, v55
	v_rcp_f32_e32 v55, v64
	v_rcp_f32_e32 v65, v65
	v_mul_f32_e32 v62, v62, v55
	v_fma_f32 v65, v65, v141, v79
	s_nop 1
	v_exp_f32_e32 v66, v48
	v_max_f32_e32 v48, v49, v49
	v_med3_f32 v48, v48, s68, v188
	v_mul_f32_e32 v48, 0xbfb8aa3b, v48
	v_exp_f32_e32 v67, v48
	v_log_f32_e32 v72, v65
	v_pk_mul_f32 v[48:49], v[62:63], v[140:141]
	v_pk_add_f32 v[64:65], v[66:67], 1.0 op_sel_hi:[1,0]
	s_nop 0
	v_rcp_f32_e32 v62, v64
	s_nop 0
	v_fma_f32 v62, v62, v128, v68
	v_log_f32_e32 v62, v62
	v_mul_f32_e32 v55, 0x3f317218, v72
	s_nop 1
	v_mul_f32_e32 v62, 0x3f317218, v62
	v_rcp_f32_e32 v63, v65
	s_nop 0
	v_mul_f32_e32 v67, v67, v63
	v_rcp_f32_e32 v63, v64
	v_rcp_f32_e32 v65, v65
	v_mul_f32_e32 v66, v66, v63
	v_fma_f32 v65, v65, v129, v69
	v_pk_mul_f32 v[66:67], v[66:67], v[128:129]
	s_nop 0
	v_pk_add_f32 v[72:73], v[50:51], 1.0 op_sel_hi:[1,0]
	v_log_f32_e32 v65, v65
	s_nop 0
	v_rcp_f32_e32 v64, v72
	s_nop 0
	v_fma_f32 v64, v64, v130, v70
	v_log_f32_e32 v64, v64
	v_mul_f32_e32 v63, 0x3f317218, v65
	s_nop 1
	v_mul_f32_e32 v64, 0x3f317218, v64
	v_rcp_f32_e32 v65, v73
	v_rcp_f32_e32 v74, v72
	v_mul_f32_e32 v51, v51, v65
	v_mul_f32_e32 v50, v50, v74
	v_rcp_f32_e32 v75, v73
	s_nop 0
	v_fma_f32 v75, v75, v131, v71
	v_pk_mul_f32 v[72:73], v[50:51], v[130:131]
	s_nop 0
	v_log_f32_e32 v75, v75
	s_nop 1
	v_mul_f32_e32 v50, 0x3f317218, v75
	v_mov_b32_e32 v65, v50
	global_store_dwordx4 v[58:59], v[52:55], off offset:512
	global_store_dwordx4 v[58:59], v[62:65], off offset:528
	v_cvt_pk_bf16_f32 v51, v48, v49
	v_exp_f32_e32 v54, v44
	v_max_f32_e32 v44, v45, v45
	v_med3_f32 v44, v44, s68, v188
	v_mul_f32_e32 v44, 0xbfb8aa3b, v44
	v_exp_f32_e32 v55, v44
	v_cvt_pk_bf16_f32 v50, v60, v61
	v_cvt_pk_bf16_f32 v52, v66, v67
	v_cvt_pk_bf16_f32 v53, v72, v73
	v_pk_add_f32 v[58:59], v[54:55], 1.0 op_sel_hi:[1,0]
	global_store_dwordx4 v[56:57], v[50:53], off offset:256
	v_add_u32_e32 v44, s45, v182
	v_rcp_f32_e32 v45, v58
	s_nop 0
	v_fma_f32 v45, v45, v166, v88
	s_nop 1
	v_log_f32_e32 v50, v45
	v_ashrrev_i32_e32 v45, 31, v44
	v_lshlrev_b64 v[44:45], 11, v[44:45]
	v_lshl_add_u64 v[48:49], v[44:45], 0, v[160:161]
	s_nop 1
	v_mul_f32_e32 v44, 0x3f317218, v50
	v_rcp_f32_e32 v45, v59
	v_rcp_f32_e32 v50, v59
	v_mul_f32_e32 v51, v55, v45
	v_fma_f32 v50, v50, v167, v89
	s_nop 1
	v_exp_f32_e32 v52, v46
	v_max_f32_e32 v46, v47, v47
	v_med3_f32 v46, v46, s68, v188
	v_mul_f32_e32 v46, 0xbfb8aa3b, v46
	v_exp_f32_e32 v53, v46
	v_log_f32_e32 v56, v50
	v_rcp_f32_e32 v45, v58
	s_nop 0
	v_mul_f32_e32 v50, v54, v45
	v_pk_mul_f32 v[50:51], v[50:51], v[166:167]
	v_pk_add_f32 v[54:55], v[52:53], 1.0 op_sel_hi:[1,0]
; DI bf16x8 pack8(const f32x4& a, const f32x4& b) { v4u w; w.x = pk2(a[0], a[1]); w.y = pk2(a[2], a[3]); w.z = pk2(b[0], b[1]); w.w = pk2(b[2], b[3]); return __builtin_bit_cast(bf16x8, w); }
;     DI void operator()(const f32x4 (&acc)[2][2][4][2], const pg8::Unit& u, int wr, int wc, int fr, int fq) const {
;     ...
;             EPI_LOOP_BEGIN
; #pragma unroll
;                 for (int bj = 0; bj < 2; ++bj) { const size_t o = (size_t)row * D + cbase + bj * 128; f32x4 lg[2], kk[2];
; #pragma unroll
;                     for (int n = 0; n < 2; ++n)
; #pragma unroll
;                         for (int e = 0; e < 4; ++e) { const float f = fminf(fmaxf(acc[ai][bj][m][n][e], -30.f), 30.f), lb = lbv[bj][n][e], ef = __expf(-f), sg = 1.f / (1.f + ef), sgn = ef / (1.f + ef);
;                             lg[n][e] = __logf(lb + (1.f - lb) * sg); kk[n][e] = (1.f - lb) * sgn; }
;                     *(f32x4*)(lf + o) = lg[0]; *(f32x4*)(lf + o + 4) = lg[1]; *(bf16x8*)(zq + (size_t)T * D + o) = pack8(kk[0], kk[1]); }
;             EPI_LOOP_END
	v_rcp_f32_e32 v46, v54
	s_nop 0
	v_fma_f32 v46, v46, v162, v90
	s_nop 0
	v_log_f32_e32 v46, v46
	v_mul_f32_e32 v45, 0x3f317218, v56
	s_nop 1
	v_mul_f32_e32 v46, 0x3f317218, v46
	v_rcp_f32_e32 v47, v55
	s_nop 0
	v_mul_f32_e32 v53, v53, v47
	v_rcp_f32_e32 v47, v54
	v_rcp_f32_e32 v55, v55
	v_mul_f32_e32 v52, v52, v47
	v_fma_f32 v55, v55, v163, v91
	s_nop 1
	v_exp_f32_e32 v56, v40
	v_max_f32_e32 v40, v41, v41
	v_med3_f32 v40, v40, s68, v188
	v_mul_f32_e32 v40, 0xbfb8aa3b, v40
	v_exp_f32_e32 v57, v40
	v_log_f32_e32 v58, v55
	v_pk_mul_f32 v[40:41], v[52:53], v[162:163]
	v_pk_add_f32 v[54:55], v[56:57], 1.0 op_sel_hi:[1,0]
	s_nop 0
	v_rcp_f32_e32 v52, v54
	s_nop 0
	v_fma_f32 v52, v52, v136, v80
	v_log_f32_e32 v52, v52
	v_mul_f32_e32 v47, 0x3f317218, v58
	s_nop 1
	v_mul_f32_e32 v52, 0x3f317218, v52
	v_rcp_f32_e32 v53, v55
	s_nop 0
	v_mul_f32_e32 v57, v57, v53
	v_rcp_f32_e32 v53, v54
	v_rcp_f32_e32 v55, v55
	v_mul_f32_e32 v56, v56, v53
	v_fma_f32 v55, v55, v137, v81
	v_pk_mul_f32 v[56:57], v[56:57], v[136:137]
	s_nop 0
	v_pk_add_f32 v[58:59], v[42:43], 1.0 op_sel_hi:[1,0]
	v_log_f32_e32 v55, v55
	s_nop 0
	v_rcp_f32_e32 v54, v58
	s_nop 0
	v_fma_f32 v54, v54, v164, v82
	v_log_f32_e32 v54, v54
	v_mul_f32_e32 v53, 0x3f317218, v55
	s_nop 1
	v_mul_f32_e32 v54, 0x3f317218, v54
	v_rcp_f32_e32 v55, v59
	v_rcp_f32_e32 v60, v58
	v_mul_f32_e32 v43, v43, v55
	v_mul_f32_e32 v42, v42, v60
	v_rcp_f32_e32 v61, v59
	s_nop 0
	v_fma_f32 v61, v61, v165, v83
	v_pk_mul_f32 v[58:59], v[42:43], v[164:165]
	v_exp_f32_e32 v60, v36
	v_log_f32_e32 v61, v61
	v_max_f32_e32 v36, v37, v37
	v_med3_f32 v36, v36, s68, v188
	v_mul_f32_e32 v36, 0xbfb8aa3b, v36
	s_nop 0
	v_mul_f32_e32 v42, 0x3f317218, v61
	v_exp_f32_e32 v61, v36
	v_mov_b32_e32 v55, v42
	v_lshl_add_u64 v[42:43], v[48:49], 2, s[18:19]
	global_store_dwordx4 v[42:43], v[44:47], off
	global_store_dwordx4 v[42:43], v[52:55], off offset:16
	s_nop 0
	v_cvt_pk_bf16_f32 v45, v40, v41
	v_pk_add_f32 v[52:53], v[60:61], 1.0 op_sel_hi:[1,0]
	v_cvt_pk_bf16_f32 v44, v50, v51
	v_cvt_pk_bf16_f32 v46, v56, v57
	v_rcp_f32_e32 v36, v52
	s_nop 0
	v_fma_f32 v36, v36, v138, v76
	v_cvt_pk_bf16_f32 v47, v58, v59
	v_lshl_add_u64 v[40:41], v[48:49], 1, s[42:43]
	v_log_f32_e32 v36, v36
	global_store_dwordx4 v[40:41], v[44:47], off
	s_nop 0
	s_nop 1
	v_mul_f32_e32 v36, 0x3f317218, v36
	v_rcp_f32_e32 v37, v53
	v_rcp_f32_e32 v44, v53
	v_mul_f32_e32 v45, v61, v37
	v_fma_f32 v44, v44, v139, v77
	s_nop 1
	v_exp_f32_e32 v46, v38
	v_max_f32_e32 v38, v39, v39
	v_med3_f32 v38, v38, s68, v188
	v_mul_f32_e32 v38, 0xbfb8aa3b, v38
	v_exp_f32_e32 v47, v38
	v_log_f32_e32 v50, v44
	v_rcp_f32_e32 v37, v52
	s_nop 0
	v_mul_f32_e32 v44, v60, v37
	v_pk_mul_f32 v[44:45], v[44:45], v[138:139]
	v_pk_add_f32 v[48:49], v[46:47], 1.0 op_sel_hi:[1,0]
	v_rcp_f32_e32 v38, v48
	s_nop 0
	v_fma_f32 v38, v38, v140, v78
	s_nop 0
	v_log_f32_e32 v38, v38
	v_mul_f32_e32 v37, 0x3f317218, v50
	s_nop 1
	v_mul_f32_e32 v38, 0x3f317218, v38
	v_rcp_f32_e32 v39, v49
	s_nop 0
	v_mul_f32_e32 v47, v47, v39
	v_rcp_f32_e32 v39, v48
	v_rcp_f32_e32 v49, v49
	v_mul_f32_e32 v46, v46, v39
	v_fma_f32 v49, v49, v141, v79
	s_nop 1
	v_exp_f32_e32 v50, v32
	v_max_f32_e32 v32, v33, v33
	v_med3_f32 v32, v32, s68, v188
	v_mul_f32_e32 v32, 0xbfb8aa3b, v32
	v_exp_f32_e32 v51, v32
	v_log_f32_e32 v52, v49
	v_pk_mul_f32 v[32:33], v[46:47], v[140:141]
	v_pk_add_f32 v[48:49], v[50:51], 1.0 op_sel_hi:[1,0]
	s_nop 0
	v_rcp_f32_e32 v46, v48
	s_nop 0
	v_fma_f32 v46, v46, v128, v68
	v_log_f32_e32 v46, v46
	v_mul_f32_e32 v39, 0x3f317218, v52
	s_nop 1
	v_mul_f32_e32 v46, 0x3f317218, v46
	v_rcp_f32_e32 v47, v49
	s_nop 0
	v_mul_f32_e32 v51, v51, v47
	v_rcp_f32_e32 v47, v48
	v_rcp_f32_e32 v49, v49
	v_mul_f32_e32 v50, v50, v47
	v_fma_f32 v49, v49, v129, v69
	v_pk_mul_f32 v[50:51], v[50:51], v[128:129]
	s_nop 0
	v_pk_add_f32 v[52:53], v[34:35], 1.0 op_sel_hi:[1,0]
	v_log_f32_e32 v49, v49
	s_nop 0
	v_rcp_f32_e32 v48, v52
	s_nop 0
	v_fma_f32 v48, v48, v130, v70
	v_log_f32_e32 v48, v48
	v_mul_f32_e32 v47, 0x3f317218, v49
	s_nop 1
	v_mul_f32_e32 v48, 0x3f317218, v48
	v_rcp_f32_e32 v49, v53
	v_rcp_f32_e32 v54, v52
	v_mul_f32_e32 v35, v35, v49
	v_mul_f32_e32 v34, v34, v54
	v_rcp_f32_e32 v55, v53
	s_nop 0
	v_fma_f32 v55, v55, v131, v71
	v_pk_mul_f32 v[52:53], v[34:35], v[130:131]
	s_nop 0
	v_log_f32_e32 v55, v55
	s_nop 1
	v_mul_f32_e32 v34, 0x3f317218, v55
	v_mov_b32_e32 v49, v34
	global_store_dwordx4 v[42:43], v[36:39], off offset:512
	global_store_dwordx4 v[42:43], v[46:49], off offset:528
	v_cvt_pk_bf16_f32 v35, v32, v33
	v_exp_f32_e32 v38, v28
	v_max_f32_e32 v28, v29, v29
	v_med3_f32 v28, v28, s68, v188
	v_mul_f32_e32 v28, 0xbfb8aa3b, v28
	v_exp_f32_e32 v39, v28
	v_cvt_pk_bf16_f32 v34, v44, v45
	v_cvt_pk_bf16_f32 v36, v50, v51
	v_cvt_pk_bf16_f32 v37, v52, v53
	v_pk_add_f32 v[42:43], v[38:39], 1.0 op_sel_hi:[1,0]
	global_store_dwordx4 v[40:41], v[34:37], off offset:256
	v_add_u32_e32 v28, s45, v183
	v_rcp_f32_e32 v29, v42
	s_nop 0
	v_fma_f32 v29, v29, v166, v88
	s_nop 1
	v_log_f32_e32 v34, v29
	v_ashrrev_i32_e32 v29, 31, v28
	v_lshlrev_b64 v[28:29], 11, v[28:29]
	v_lshl_add_u64 v[32:33], v[28:29], 0, v[160:161]
	s_nop 1
	v_mul_f32_e32 v28, 0x3f317218, v34
	v_rcp_f32_e32 v29, v43
	v_rcp_f32_e32 v34, v43
	v_mul_f32_e32 v35, v39, v29
	v_fma_f32 v34, v34, v167, v89
	s_nop 1
	v_exp_f32_e32 v36, v30
	v_max_f32_e32 v30, v31, v31
	v_med3_f32 v30, v30, s68, v188
	v_mul_f32_e32 v30, 0xbfb8aa3b, v30
	v_exp_f32_e32 v37, v30
	v_log_f32_e32 v40, v34
	v_rcp_f32_e32 v29, v42
	s_nop 0
	v_mul_f32_e32 v34, v38, v29
	v_pk_mul_f32 v[34:35], v[34:35], v[166:167]
	v_pk_add_f32 v[38:39], v[36:37], 1.0 op_sel_hi:[1,0]
	v_rcp_f32_e32 v30, v38
	s_nop 0
; DI bf16x8 pack8(const f32x4& a, const f32x4& b) { v4u w; w.x = pk2(a[0], a[1]); w.y = pk2(a[2], a[3]); w.z = pk2(b[0], b[1]); w.w = pk2(b[2], b[3]); return __builtin_bit_cast(bf16x8, w); }
;     DI void operator()(const f32x4 (&acc)[2][2][4][2], const pg8::Unit& u, int wr, int wc, int fr, int fq) const {
;     ...
;             EPI_LOOP_BEGIN
; #pragma unroll
;                 for (int bj = 0; bj < 2; ++bj) { const size_t o = (size_t)row * D + cbase + bj * 128; f32x4 lg[2], kk[2];
; #pragma unroll
;                     for (int n = 0; n < 2; ++n)
; #pragma unroll
;                         for (int e = 0; e < 4; ++e) { const float f = fminf(fmaxf(acc[ai][bj][m][n][e], -30.f), 30.f), lb = lbv[bj][n][e], ef = __expf(-f), sg = 1.f / (1.f + ef), sgn = ef / (1.f + ef);
;                             lg[n][e] = __logf(lb + (1.f - lb) * sg); kk[n][e] = (1.f - lb) * sgn; }
;                     *(f32x4*)(lf + o) = lg[0]; *(f32x4*)(lf + o + 4) = lg[1]; *(bf16x8*)(zq + (size_t)T * D + o) = pack8(kk[0], kk[1]); }
;             EPI_LOOP_END
	v_fma_f32 v30, v30, v162, v90
	s_nop 0
	v_log_f32_e32 v30, v30
	v_mul_f32_e32 v29, 0x3f317218, v40
	s_nop 1
	v_mul_f32_e32 v30, 0x3f317218, v30
	v_rcp_f32_e32 v31, v39
	s_nop 0
	v_mul_f32_e32 v37, v37, v31
	v_rcp_f32_e32 v31, v38
	v_rcp_f32_e32 v39, v39
	v_mul_f32_e32 v36, v36, v31
	v_fma_f32 v39, v39, v163, v91
	s_nop 1
	v_exp_f32_e32 v40, v24
	v_max_f32_e32 v24, v25, v25
	v_med3_f32 v24, v24, s68, v188
	v_mul_f32_e32 v24, 0xbfb8aa3b, v24
	v_exp_f32_e32 v41, v24
	v_log_f32_e32 v42, v39
	v_pk_mul_f32 v[24:25], v[36:37], v[162:163]
	v_pk_add_f32 v[38:39], v[40:41], 1.0 op_sel_hi:[1,0]
	s_nop 0
	v_rcp_f32_e32 v36, v38
	s_nop 0
	v_fma_f32 v36, v36, v136, v80
	v_log_f32_e32 v36, v36
	v_mul_f32_e32 v31, 0x3f317218, v42
	s_nop 1
	v_mul_f32_e32 v36, 0x3f317218, v36
	v_rcp_f32_e32 v37, v39
	s_nop 0
	v_mul_f32_e32 v41, v41, v37
	v_rcp_f32_e32 v37, v38
	v_rcp_f32_e32 v39, v39
	v_mul_f32_e32 v40, v40, v37
	v_fma_f32 v39, v39, v137, v81
	v_pk_mul_f32 v[40:41], v[40:41], v[136:137]
	s_nop 0
	v_pk_add_f32 v[42:43], v[26:27], 1.0 op_sel_hi:[1,0]
	v_log_f32_e32 v39, v39
	s_nop 0
	v_rcp_f32_e32 v38, v42
	s_nop 0
	v_fma_f32 v38, v38, v164, v82
	v_log_f32_e32 v38, v38
	v_mul_f32_e32 v37, 0x3f317218, v39
	s_nop 1
	v_mul_f32_e32 v38, 0x3f317218, v38
	v_rcp_f32_e32 v39, v43
	v_rcp_f32_e32 v44, v42
	v_mul_f32_e32 v27, v27, v39
	v_mul_f32_e32 v26, v26, v44
	v_rcp_f32_e32 v45, v43
	s_nop 0
	v_fma_f32 v45, v45, v165, v83
	v_pk_mul_f32 v[42:43], v[26:27], v[164:165]
	v_exp_f32_e32 v44, v20
	v_log_f32_e32 v45, v45
	v_max_f32_e32 v20, v21, v21
	v_med3_f32 v20, v20, s68, v188
	v_mul_f32_e32 v20, 0xbfb8aa3b, v20
	s_nop 0
	v_mul_f32_e32 v26, 0x3f317218, v45
	v_exp_f32_e32 v45, v20
	v_mov_b32_e32 v39, v26
	v_lshl_add_u64 v[26:27], v[32:33], 2, s[18:19]
	global_store_dwordx4 v[26:27], v[28:31], off
	global_store_dwordx4 v[26:27], v[36:39], off offset:16
	s_nop 0
	v_cvt_pk_bf16_f32 v29, v24, v25
	v_pk_add_f32 v[36:37], v[44:45], 1.0 op_sel_hi:[1,0]
	v_cvt_pk_bf16_f32 v28, v34, v35
	v_cvt_pk_bf16_f32 v30, v40, v41
	v_rcp_f32_e32 v20, v36
	s_nop 0
	v_fma_f32 v20, v20, v138, v76
	v_cvt_pk_bf16_f32 v31, v42, v43
	v_lshl_add_u64 v[24:25], v[32:33], 1, s[42:43]
	v_log_f32_e32 v20, v20
	global_store_dwordx4 v[24:25], v[28:31], off
	s_nop 0
	s_nop 1
	v_mul_f32_e32 v20, 0x3f317218, v20
	v_rcp_f32_e32 v21, v37
	v_rcp_f32_e32 v28, v37
	v_mul_f32_e32 v29, v45, v21
	v_fma_f32 v28, v28, v139, v77
	s_nop 1
	v_exp_f32_e32 v30, v22
	v_max_f32_e32 v22, v23, v23
	v_med3_f32 v22, v22, s68, v188
	v_mul_f32_e32 v22, 0xbfb8aa3b, v22
	v_exp_f32_e32 v31, v22
	v_log_f32_e32 v34, v28
	v_rcp_f32_e32 v21, v36
	s_nop 0
	v_mul_f32_e32 v28, v44, v21
	v_pk_mul_f32 v[28:29], v[28:29], v[138:139]
	v_pk_add_f32 v[32:33], v[30:31], 1.0 op_sel_hi:[1,0]
	v_rcp_f32_e32 v22, v32
	s_nop 0
	v_fma_f32 v22, v22, v140, v78
	s_nop 0
	v_log_f32_e32 v22, v22
	v_mul_f32_e32 v21, 0x3f317218, v34
	s_nop 1
	v_mul_f32_e32 v22, 0x3f317218, v22
	v_rcp_f32_e32 v23, v33
	s_nop 0
	v_mul_f32_e32 v31, v31, v23
	v_rcp_f32_e32 v23, v32
	v_rcp_f32_e32 v33, v33
	v_mul_f32_e32 v30, v30, v23
	v_fma_f32 v33, v33, v141, v79
	s_nop 1
	v_exp_f32_e32 v34, v16
	v_max_f32_e32 v16, v17, v17
	v_med3_f32 v16, v16, s68, v188
	v_mul_f32_e32 v16, 0xbfb8aa3b, v16
	v_exp_f32_e32 v35, v16
	v_log_f32_e32 v36, v33
	v_pk_mul_f32 v[16:17], v[30:31], v[140:141]
	v_pk_add_f32 v[32:33], v[34:35], 1.0 op_sel_hi:[1,0]
	s_nop 0
	v_rcp_f32_e32 v30, v32
	s_nop 0
	v_fma_f32 v30, v30, v128, v68
	v_log_f32_e32 v30, v30
	v_mul_f32_e32 v23, 0x3f317218, v36
	s_nop 1
	v_mul_f32_e32 v30, 0x3f317218, v30
	v_rcp_f32_e32 v31, v33
	s_nop 0
	v_mul_f32_e32 v35, v35, v31
	v_rcp_f32_e32 v31, v32
	v_rcp_f32_e32 v33, v33
	v_mul_f32_e32 v34, v34, v31
	v_fma_f32 v33, v33, v129, v69
	v_pk_mul_f32 v[34:35], v[34:35], v[128:129]
	s_nop 0
	v_pk_add_f32 v[36:37], v[18:19], 1.0 op_sel_hi:[1,0]
	v_log_f32_e32 v33, v33
	s_nop 0
	v_rcp_f32_e32 v32, v36
	s_nop 0
	v_fma_f32 v32, v32, v130, v70
	v_log_f32_e32 v32, v32
	v_mul_f32_e32 v31, 0x3f317218, v33
	s_nop 1
	v_mul_f32_e32 v32, 0x3f317218, v32
	v_rcp_f32_e32 v33, v37
	v_rcp_f32_e32 v38, v36
	v_mul_f32_e32 v19, v19, v33
	v_mul_f32_e32 v18, v18, v38
	v_rcp_f32_e32 v39, v37
	s_nop 0
	v_fma_f32 v39, v39, v131, v71
	v_pk_mul_f32 v[36:37], v[18:19], v[130:131]
	s_nop 0
	v_log_f32_e32 v39, v39
	s_nop 1
	v_mul_f32_e32 v18, 0x3f317218, v39
	v_mov_b32_e32 v33, v18
	global_store_dwordx4 v[26:27], v[20:23], off offset:512
	global_store_dwordx4 v[26:27], v[30:33], off offset:528
	v_cvt_pk_bf16_f32 v19, v16, v17
	v_exp_f32_e32 v22, v12
	v_max_f32_e32 v12, v13, v13
	v_med3_f32 v12, v12, s68, v188
	v_mul_f32_e32 v12, 0xbfb8aa3b, v12
	v_exp_f32_e32 v23, v12
	v_cvt_pk_bf16_f32 v18, v28, v29
	v_cvt_pk_bf16_f32 v20, v34, v35
	v_cvt_pk_bf16_f32 v21, v36, v37
	v_pk_add_f32 v[26:27], v[22:23], 1.0 op_sel_hi:[1,0]
	global_store_dwordx4 v[24:25], v[18:21], off offset:256
	v_add_u32_e32 v12, s45, v184
	v_rcp_f32_e32 v13, v26
	s_nop 0
	v_fma_f32 v13, v13, v166, v88
	s_nop 1
	v_log_f32_e32 v18, v13
	v_ashrrev_i32_e32 v13, 31, v12
	v_lshlrev_b64 v[12:13], 11, v[12:13]
	v_lshl_add_u64 v[16:17], v[12:13], 0, v[160:161]
	s_nop 1
; DI bf16x8 pack8(const f32x4& a, const f32x4& b) { v4u w; w.x = pk2(a[0], a[1]); w.y = pk2(a[2], a[3]); w.z = pk2(b[0], b[1]); w.w = pk2(b[2], b[3]); return __builtin_bit_cast(bf16x8, w); }
;     DI void operator()(const f32x4 (&acc)[2][2][4][2], const pg8::Unit& u, int wr, int wc, int fr, int fq) const {
;     ...
;             EPI_LOOP_BEGIN
; #pragma unroll
;                 for (int bj = 0; bj < 2; ++bj) { const size_t o = (size_t)row * D + cbase + bj * 128; f32x4 lg[2], kk[2];
; #pragma unroll
;                     for (int n = 0; n < 2; ++n)
; #pragma unroll
;                         for (int e = 0; e < 4; ++e) { const float f = fminf(fmaxf(acc[ai][bj][m][n][e], -30.f), 30.f), lb = lbv[bj][n][e], ef = __expf(-f), sg = 1.f / (1.f + ef), sgn = ef / (1.f + ef);
;                             lg[n][e] = __logf(lb + (1.f - lb) * sg); kk[n][e] = (1.f - lb) * sgn; }
;                     *(f32x4*)(lf + o) = lg[0]; *(f32x4*)(lf + o + 4) = lg[1]; *(bf16x8*)(zq + (size_t)T * D + o) = pack8(kk[0], kk[1]); }
;             EPI_LOOP_END
	v_mul_f32_e32 v12, 0x3f317218, v18
	v_rcp_f32_e32 v13, v27
	v_rcp_f32_e32 v18, v27
	v_mul_f32_e32 v19, v23, v13
	v_fma_f32 v18, v18, v167, v89
	s_nop 1
	v_exp_f32_e32 v20, v14
	v_max_f32_e32 v14, v15, v15
	v_med3_f32 v14, v14, s68, v188
	v_mul_f32_e32 v14, 0xbfb8aa3b, v14
	v_exp_f32_e32 v21, v14
	v_log_f32_e32 v24, v18
	v_rcp_f32_e32 v13, v26
	s_nop 0
	v_mul_f32_e32 v18, v22, v13
	v_pk_mul_f32 v[18:19], v[18:19], v[166:167]
	v_pk_add_f32 v[22:23], v[20:21], 1.0 op_sel_hi:[1,0]
	v_rcp_f32_e32 v14, v22
	s_nop 0
	v_fma_f32 v14, v14, v162, v90
	s_nop 0
	v_log_f32_e32 v14, v14
	v_mul_f32_e32 v13, 0x3f317218, v24
	s_nop 1
	v_mul_f32_e32 v14, 0x3f317218, v14
	v_rcp_f32_e32 v15, v23
	s_nop 0
	v_mul_f32_e32 v21, v21, v15
	v_rcp_f32_e32 v15, v22
	v_rcp_f32_e32 v23, v23
	v_mul_f32_e32 v20, v20, v15
	v_pk_add_f32 v[24:25], v[8:9], 1.0 op_sel_hi:[1,0]
	v_fmac_f32_e32 v91, v23, v163
	v_pk_mul_f32 v[20:21], v[20:21], v[162:163]
	s_nop 0
	v_log_f32_e32 v23, v91
	v_rcp_f32_e32 v22, v24
	s_nop 0
	v_fma_f32 v22, v22, v136, v80
	v_log_f32_e32 v22, v22
	s_nop 1
	v_mul_f32_e32 v15, 0x3f317218, v23
	s_nop 1
	v_mul_f32_e32 v22, 0x3f317218, v22
	v_rcp_f32_e32 v23, v25
	s_nop 0
	v_mul_f32_e32 v9, v9, v23
	v_rcp_f32_e32 v23, v24
	v_rcp_f32_e32 v25, v25
	v_mul_f32_e32 v8, v8, v23
	v_fma_f32 v25, v25, v137, v81
	s_nop 1
	v_pk_mul_f32 v[26:27], v[8:9], v[136:137]
	v_pk_add_f32 v[8:9], v[10:11], 1.0 op_sel_hi:[1,0]
	v_log_f32_e32 v25, v25
	s_nop 0
	v_rcp_f32_e32 v24, v8
	s_nop 0
	v_fma_f32 v24, v24, v164, v82
	v_log_f32_e32 v24, v24
	v_mul_f32_e32 v23, 0x3f317218, v25
	s_nop 1
	v_mul_f32_e32 v24, 0x3f317218, v24
	v_rcp_f32_e32 v28, v8
	v_rcp_f32_e32 v29, v9
	v_mul_f32_e32 v8, v10, v28
	v_fmac_f32_e32 v83, v29, v165
	v_rcp_f32_e32 v25, v9
	s_nop 0
	v_mul_f32_e32 v9, v11, v25
	v_pk_mul_f32 v[10:11], v[8:9], v[164:165]
	v_log_f32_e32 v29, v83
	v_exp_f32_e32 v28, v4
	v_max_f32_e32 v4, v5, v5
	v_med3_f32 v4, v4, s68, v188
	v_mul_f32_e32 v4, 0xbfb8aa3b, v4
	v_mul_f32_e32 v8, 0x3f317218, v29
	v_exp_f32_e32 v29, v4
	v_mov_b32_e32 v25, v8
	v_lshl_add_u64 v[8:9], v[16:17], 2, s[18:19]
	global_store_dwordx4 v[8:9], v[12:15], off
	global_store_dwordx4 v[8:9], v[22:25], off offset:16
	s_nop 0
	v_cvt_pk_bf16_f32 v12, v18, v19
	v_pk_add_f32 v[22:23], v[28:29], 1.0 op_sel_hi:[1,0]
	v_cvt_pk_bf16_f32 v13, v20, v21
	v_cvt_pk_bf16_f32 v14, v26, v27
	v_rcp_f32_e32 v4, v22
	s_nop 0
	v_fma_f32 v4, v4, v138, v76
	v_cvt_pk_bf16_f32 v15, v10, v11
	v_lshl_add_u64 v[10:11], v[16:17], 1, s[42:43]
	v_log_f32_e32 v4, v4
	global_store_dwordx4 v[10:11], v[12:15], off
	s_nop 0
	s_nop 1
	v_mul_f32_e32 v4, 0x3f317218, v4
	v_rcp_f32_e32 v5, v23
	v_rcp_f32_e32 v12, v23
	v_mul_f32_e32 v13, v29, v5
	v_fma_f32 v12, v12, v139, v77
	s_nop 1
	v_exp_f32_e32 v14, v6
	v_max_f32_e32 v6, v7, v7
	v_med3_f32 v6, v6, s68, v188
	v_mul_f32_e32 v6, 0xbfb8aa3b, v6
	v_exp_f32_e32 v15, v6
	v_log_f32_e32 v18, v12
	v_rcp_f32_e32 v5, v22
	s_nop 0
	v_mul_f32_e32 v12, v28, v5
	v_pk_mul_f32 v[12:13], v[12:13], v[138:139]
	v_pk_add_f32 v[16:17], v[14:15], 1.0 op_sel_hi:[1,0]
	v_rcp_f32_e32 v6, v16
	s_nop 0
	v_fma_f32 v6, v6, v140, v78
	s_nop 0
	v_log_f32_e32 v6, v6
	v_mul_f32_e32 v5, 0x3f317218, v18
	s_nop 1
	v_mul_f32_e32 v6, 0x3f317218, v6
	v_rcp_f32_e32 v7, v17
	s_nop 0
	v_mul_f32_e32 v15, v15, v7
	v_rcp_f32_e32 v7, v16
	v_rcp_f32_e32 v17, v17
	v_mul_f32_e32 v14, v14, v7
	v_exp_f32_e32 v18, v0
	v_max_f32_e32 v0, v1, v1
	v_med3_f32 v0, v0, s68, v188
	v_mul_f32_e32 v0, 0xbfb8aa3b, v0
	v_fmac_f32_e32 v79, v17, v141
	v_exp_f32_e32 v19, v0
	v_pk_mul_f32 v[14:15], v[14:15], v[140:141]
	s_nop 0
	v_log_f32_e32 v20, v79
	v_pk_add_f32 v[16:17], v[18:19], 1.0 op_sel_hi:[1,0]
	v_rcp_f32_e32 v1, v16
	s_nop 0
	v_fma_f32 v1, v1, v128, v68
	s_nop 0
	v_log_f32_e32 v1, v1
	v_mul_f32_e32 v0, 0x3f317218, v20
	v_mov_b32_e32 v7, v0
	s_nop 1
	v_mul_f32_e32 v0, 0x3f317218, v1
	v_rcp_f32_e32 v1, v17
	s_nop 0
	v_mul_f32_e32 v19, v19, v1
	v_rcp_f32_e32 v1, v16
	v_rcp_f32_e32 v17, v17
	v_mul_f32_e32 v18, v18, v1
	v_fma_f32 v17, v17, v129, v69
	s_nop 1
	v_exp_f32_e32 v20, v2
	v_max_f32_e32 v2, v3, v3
	v_med3_f32 v2, v2, s68, v188
	v_mul_f32_e32 v2, 0xbfb8aa3b, v2
	v_exp_f32_e32 v21, v2
	v_log_f32_e32 v22, v17
	v_pk_mul_f32 v[16:17], v[18:19], v[128:129]
	v_pk_add_f32 v[18:19], v[20:21], 1.0 op_sel_hi:[1,0]
	s_nop 0
	v_rcp_f32_e32 v2, v18
	s_nop 0
	v_fma_f32 v2, v2, v130, v70
	v_log_f32_e32 v2, v2
	v_mul_f32_e32 v1, 0x3f317218, v22
	s_nop 1
	v_mul_f32_e32 v2, 0x3f317218, v2
	v_rcp_f32_e32 v22, v18
	v_rcp_f32_e32 v23, v19
	v_mul_f32_e32 v18, v20, v22
	v_fmac_f32_e32 v71, v23, v131
	v_rcp_f32_e32 v3, v19
	s_nop 0
	v_mul_f32_e32 v19, v21, v3
	v_pk_mul_f32 v[18:19], v[18:19], v[130:131]
	v_log_f32_e32 v23, v71
	s_nop 1
	v_mul_f32_e32 v3, 0x3f317218, v23
	global_store_dwordx4 v[8:9], v[4:7], off offset:512
	global_store_dwordx4 v[8:9], v[0:3], off offset:528
	s_nop 1
	v_cvt_pk_bf16_f32 v0, v12, v13
	v_cvt_pk_bf16_f32 v1, v14, v15
	v_cvt_pk_bf16_f32 v2, v16, v17
	v_cvt_pk_bf16_f32 v3, v18, v19
	global_store_dwordx4 v[10:11], v[0:3], off offset:256
	s_andn2_b64 vcc, exec, s[4:5]
	s_mov_b64 s[4:5], -1
	s_cbranch_vccnz .LBB0_222

; #define LAS __attribute__((address_space(3)))
; #define IX_PF_LOAD(h_) do { if (more) { _Pragma("unroll") for (int it = 0; it < 2; ++it) { const int ci = tid + 512 * (2 * (h_) + it), row = ci >> 4, ch = ci & 15; st[it] = *(const v4u*)(KIB + (size_t)(128 * ns + row) * 128 + 8 * ch); } } } while (0)
; #define IX_PF_STORE(h_) do { if (more) { _Pragma("unroll") for (int it = 0; it < 2; ++it) { const int ci = tid + 512 * (2 * (h_) + it), row = ci >> 4, ch = ci & 15; *(LAS v4u*)(NBUF + row * 272 + 16 * ch) = st[it]; } } } while (0)
; #define IX_CHAIN(acc_, a_) do { _Pragma("unroll") for (int i_ = 0; i_ < 16; ++i_) acc_[i_] = 0.f; __builtin_amdgcn_s_setprio(1); _Pragma("unroll") for (int s_ = 0; s_ < 8; ++s_) acc_ = MFMA32(af[a_][s_], bfr[s_], acc_); __builtin_amdgcn_s_setprio(0); } while (0)
; DI void indexer_prompt(LAS unsigned char* lds, const bf16* QIB, const bf16* KIB, const float* WI, float* SC, int bid, int G, int tid_) {
;     ...
;         LAS unsigned char* NBUF = lds + IX_ST0 + (((item - lo) & 1) ^ 1) * IX_STB;
;     ...
;         IX_PF_LOAD(0);
;         f32x2 wn = (f32x2){0.f, 0.f};
;         if (more && nqb != qb) wn = *(const f32x2*)(WI + (size_t)(64 * nqb) * 16 + 2 * tid);
;         const int qlast_w = q0 + 8 * wave + 7;
;         const int par = (item - lo) & 1;
;         LAS unsigned char* SB = lds + IX_ST0 + par * IX_STB;
;         LAS unsigned char* WBUF = lds + (wsel ? IX_W2 : IX_W);
; #pragma unroll
;         for (int bt = 0; bt < 4; ++bt) {
;             const int key0 = k0s + 32 * bt;
;             if (bt == 2) { IX_PF_STORE(0); IX_PF_LOAD(1); }
;             if (key0 <= qlast_w) {
;             bf16x8 bfr[8];
; #pragma unroll
;             for (int s_ = 0; s_ < 8; ++s_) bfr[s_] = *(const LAS bf16x8*)(SB + (32 * bt + m) * 272 + 32 * s_ + 16 * hh);
;             f32x16 accA;
;     ...
;             IX_CHAIN(accA, 0); IX_EPI(accA, 0);
.LBB0_1510:
	s_mov_b32 s100, 0
	s_mov_b32 s101, 0
	s_and_b32 s41, s35, 1
	s_lshl_b32 s20, s18, 7
	s_add_i32 s21, s19, s31
	s_mul_i32 s18, s41, 0x8800
	s_or_b32 s12, s21, 7
	s_add_i32 s42, s18, 0
	s_cmp_eq_u32 s37, 0
	s_cselect_b64 s[18:19], -1, 0
	s_and_b64 s[22:23], s[18:19], exec
	s_cselect_b32 s22, 0, 0x12000
	s_add_i32 s22, s22, 0
	v_lshl_add_u32 v5, v0, 4, s42
	v_or_b32_e32 v1, s31, v0
	v_or_b32_e32 v0, s21, v0
	v_lshl_add_u32 v169, v1, 6, s22
	v_ashrrev_i32_e32 v1, 31, v0
	v_and_b32_e32 v4, 31, v171
	v_lshlrev_b64 v[2:3], 15, v[0:1]
	v_lshl_add_u64 v[2:3], s[10:11], 0, v[2:3]
	v_lshlrev_b32_e32 v152, 2, v4
	v_lshl_add_u64 v[162:163], v[2:3], 0, v[152:153]
	v_or_b32_e32 v2, 2, v0
	v_ashrrev_i32_e32 v3, 31, v2
	v_lshlrev_b64 v[2:3], 15, v[2:3]
	v_lshl_add_u64 v[2:3], s[10:11], 0, v[2:3]
	v_lshl_add_u64 v[160:161], v[2:3], 0, v[152:153]
	v_or_b32_e32 v2, 4, v0
	v_or_b32_e32 v0, 6, v0
	v_ashrrev_i32_e32 v3, 31, v2
	v_ashrrev_i32_e32 v1, 31, v0
	v_lshlrev_b64 v[2:3], 15, v[2:3]
	v_lshlrev_b64 v[0:1], 15, v[0:1]
	v_lshl_add_u64 v[2:3], s[10:11], 0, v[2:3]
	v_lshl_add_u64 v[0:1], s[10:11], 0, v[0:1]
	v_lshl_add_u64 v[158:159], v[2:3], 0, v[152:153]
	v_lshl_add_u64 v[156:157], v[0:1], 0, v[152:153]
	s_cmp_le_i32 s20, s12
	v_mad_u32_u24 v170, v4, s34, v5
	s_cbranch_scc0 .LBB0_1512
	ds_read_b128 v[174:177], v170 offset:4096
	ds_read_b128 v[178:181], v170 offset:4128
	ds_read_b128 v[182:185], v170 offset:4160
	ds_read_b128 v[186:189], v170 offset:4192
	ds_read_b128 v[190:193], v170 offset:4224
	ds_read_b128 v[194:197], v170 offset:4256
	ds_read_b128 v[198:201], v170 offset:4288
	ds_read_b128 v[202:205], v170 offset:4320
	s_setprio 1
	s_waitcnt lgkmcnt(7)
	v_mfma_f32_32x32x16_bf16 v[0:15], v[44:47], v[174:177], 0
	s_waitcnt lgkmcnt(6)
	v_mfma_f32_32x32x16_bf16 v[0:15], v[40:43], v[178:181], v[0:15]
	s_waitcnt lgkmcnt(5)
	v_mfma_f32_32x32x16_bf16 v[0:15], v[36:39], v[182:185], v[0:15]
	s_waitcnt lgkmcnt(4)
	v_mfma_f32_32x32x16_bf16 v[0:15], v[32:35], v[186:189], v[0:15]
	s_waitcnt lgkmcnt(3)
	v_mfma_f32_32x32x16_bf16 v[0:15], v[28:31], v[190:193], v[0:15]
	s_waitcnt lgkmcnt(2)
	v_mfma_f32_32x32x16_bf16 v[0:15], v[24:27], v[194:197], v[0:15]
	s_waitcnt lgkmcnt(1)
	v_mfma_f32_32x32x16_bf16 v[0:15], v[20:23], v[198:201], v[0:15]
	s_waitcnt lgkmcnt(0)
	v_mfma_f32_32x32x16_bf16 v[0:15], v[16:19], v[202:205], v[0:15]
	ds_read_b128 v[206:209], v169
	ds_read_b128 v[210:213], v169 offset:16
	ds_read_b128 v[214:217], v169 offset:32
	ds_read_b128 v[218:221], v169 offset:48
	v_mfma_f32_32x32x16_bf16 v[224:239], v[76:79], v[174:177], 0
	v_mfma_f32_32x32x16_bf16 v[224:239], v[72:75], v[178:181], v[224:239]
	v_mfma_f32_32x32x16_bf16 v[224:239], v[68:71], v[182:185], v[224:239]
	v_mfma_f32_32x32x16_bf16 v[224:239], v[64:67], v[186:189], v[224:239]
	s_nop 3
	v_med3_f32 v0, v0, 0, v167
	s_waitcnt lgkmcnt(3)
	v_med3_f32 v1, v1, 0, v167
	v_med3_f32 v2, v2, 0, v167
	v_pk_mul_f32 v[0:1], v[0:1], v[206:207]
	v_med3_f32 v3, v3, 0, v167
	v_mfma_f32_32x32x16_bf16 v[224:239], v[60:63], v[190:193], v[224:239]
	v_pk_fma_f32 v[0:1], v[2:3], v[208:209], v[0:1]
	v_med3_f32 v4, v4, 0, v167
	s_waitcnt lgkmcnt(2)
	v_med3_f32 v5, v5, 0, v167
	v_pk_fma_f32 v[0:1], v[4:5], v[210:211], v[0:1]
	v_med3_f32 v6, v6, 0, v167
	v_mfma_f32_32x32x16_bf16 v[224:239], v[56:59], v[194:197], v[224:239]
	v_med3_f32 v7, v7, 0, v167
	v_pk_fma_f32 v[0:1], v[6:7], v[212:213], v[0:1]
	v_med3_f32 v8, v8, 0, v167
	s_waitcnt lgkmcnt(1)
	v_med3_f32 v9, v9, 0, v167
	v_pk_fma_f32 v[0:1], v[8:9], v[214:215], v[0:1]
	v_med3_f32 v10, v10, 0, v167
	v_mfma_f32_32x32x16_bf16 v[224:239], v[52:55], v[198:201], v[224:239]
	v_med3_f32 v11, v11, 0, v167
	v_pk_fma_f32 v[0:1], v[10:11], v[216:217], v[0:1]
	v_med3_f32 v12, v12, 0, v167
	s_waitcnt lgkmcnt(0)
	v_med3_f32 v13, v13, 0, v167
	v_pk_fma_f32 v[0:1], v[12:13], v[218:219], v[0:1]
	v_mfma_f32_32x32x16_bf16 v[224:239], v[48:51], v[202:205], v[224:239]
	v_med3_f32 v14, v14, 0, v167
	v_med3_f32 v15, v15, 0, v167
	s_ashr_i32 s21, s20, 31
	v_pk_fma_f32 v[0:1], v[14:15], v[220:221], v[0:1]
	s_lshl_b64 s[22:23], s[20:21], 2
	v_add_f32_e32 v2, v0, v1
	v_lshl_add_u64 v[0:1], v[162:163], 0, s[22:23]
	global_store_dword v[0:1], v2, off
	ds_read_b128 v[206:209], v169 offset:128
	ds_read_b128 v[210:213], v169 offset:144
	ds_read_b128 v[214:217], v169 offset:160
	ds_read_b128 v[218:221], v169 offset:176
	v_mfma_f32_32x32x16_bf16 v[0:15], v[108:111], v[174:177], 0
	v_mfma_f32_32x32x16_bf16 v[0:15], v[104:107], v[178:181], v[0:15]
	v_mfma_f32_32x32x16_bf16 v[0:15], v[100:103], v[182:185], v[0:15]
	v_mfma_f32_32x32x16_bf16 v[0:15], v[96:99], v[186:189], v[0:15]
	s_nop 3
	v_med3_f32 v224, v224, 0, v167
	s_waitcnt lgkmcnt(3)
	v_med3_f32 v225, v225, 0, v167
	v_med3_f32 v226, v226, 0, v167
	v_pk_mul_f32 v[224:225], v[224:225], v[206:207]
	v_med3_f32 v227, v227, 0, v167
	v_mfma_f32_32x32x16_bf16 v[0:15], v[92:95], v[190:193], v[0:15]
	v_pk_fma_f32 v[224:225], v[226:227], v[208:209], v[224:225]
	v_med3_f32 v228, v228, 0, v167
	s_waitcnt lgkmcnt(2)
	v_med3_f32 v229, v229, 0, v167
	v_pk_fma_f32 v[224:225], v[228:229], v[210:211], v[224:225]
	v_med3_f32 v230, v230, 0, v167
	v_mfma_f32_32x32x16_bf16 v[0:15], v[88:91], v[194:197], v[0:15]
	v_med3_f32 v231, v231, 0, v167
	v_pk_fma_f32 v[224:225], v[230:231], v[212:213], v[224:225]
	v_med3_f32 v232, v232, 0, v167
	s_waitcnt lgkmcnt(1)
	v_med3_f32 v233, v233, 0, v167
	v_pk_fma_f32 v[224:225], v[232:233], v[214:215], v[224:225]
	v_med3_f32 v234, v234, 0, v167
	v_mfma_f32_32x32x16_bf16 v[0:15], v[84:87], v[198:201], v[0:15]
	v_med3_f32 v235, v235, 0, v167
	v_pk_fma_f32 v[224:225], v[234:235], v[216:217], v[224:225]
	v_med3_f32 v236, v236, 0, v167
	s_waitcnt lgkmcnt(0)
; #define LAS __attribute__((address_space(3)))
; #define IX_PF_LOAD(h_) do { if (more) { _Pragma("unroll") for (int it = 0; it < 2; ++it) { const int ci = tid + 512 * (2 * (h_) + it), row = ci >> 4, ch = ci & 15; st[it] = *(const v4u*)(KIB + (size_t)(128 * ns + row) * 128 + 8 * ch); } } } while (0)
; #define IX_PF_STORE(h_) do { if (more) { _Pragma("unroll") for (int it = 0; it < 2; ++it) { const int ci = tid + 512 * (2 * (h_) + it), row = ci >> 4, ch = ci & 15; *(LAS v4u*)(NBUF + row * 272 + 16 * ch) = st[it]; } } } while (0)
; #define IX_CHAIN(acc_, a_) do { _Pragma("unroll") for (int i_ = 0; i_ < 16; ++i_) acc_[i_] = 0.f; __builtin_amdgcn_s_setprio(1); _Pragma("unroll") for (int s_ = 0; s_ < 8; ++s_) acc_ = MFMA32(af[a_][s_], bfr[s_], acc_); __builtin_amdgcn_s_setprio(0); } while (0)
; DI void indexer_prompt(LAS unsigned char* lds, const bf16* QIB, const bf16* KIB, const float* WI, float* SC, int bid, int G, int tid_) {
;     ...
;         for (int bt = 0; bt < 4; ++bt) {
;             const int key0 = k0s + 32 * bt;
;             if (bt == 2) { IX_PF_STORE(0); IX_PF_LOAD(1); }
;             if (key0 <= qlast_w) {
;             bf16x8 bfr[8];
; #pragma unroll
;             for (int s_ = 0; s_ < 8; ++s_) bfr[s_] = *(const LAS bf16x8*)(SB + (32 * bt + m) * 272 + 32 * s_ + 16 * hh);
;             f32x16 accA;
;     ...
;             IX_CHAIN(accA, 0); IX_EPI(accA, 0);
;             IX_CHAIN(accA, 1); IX_EPI(accA, 1);
;             IX_CHAIN(accA, 2); IX_EPI(accA, 2);
;             IX_CHAIN(accA, 3); IX_EPI(accA, 3);
	v_med3_f32 v237, v237, 0, v167
	v_pk_fma_f32 v[224:225], v[236:237], v[218:219], v[224:225]
	v_mfma_f32_32x32x16_bf16 v[0:15], v[80:83], v[202:205], v[0:15]
	v_med3_f32 v238, v238, 0, v167
	v_med3_f32 v239, v239, 0, v167
	v_pk_fma_f32 v[224:225], v[238:239], v[220:221], v[224:225]
	v_add_f32_e32 v226, v224, v225
	v_lshl_add_u64 v[224:225], v[160:161], 0, s[22:23]
	global_store_dword v[224:225], v226, off
	ds_read_b128 v[206:209], v169 offset:256
	ds_read_b128 v[210:213], v169 offset:272
	ds_read_b128 v[214:217], v169 offset:288
	ds_read_b128 v[218:221], v169 offset:304
	v_mfma_f32_32x32x16_bf16 v[224:239], v[148:151], v[174:177], 0
	v_mfma_f32_32x32x16_bf16 v[224:239], v[144:147], v[178:181], v[224:239]
	v_mfma_f32_32x32x16_bf16 v[224:239], v[140:143], v[182:185], v[224:239]
	v_mfma_f32_32x32x16_bf16 v[224:239], v[136:139], v[186:189], v[224:239]
	s_nop 3
	v_med3_f32 v0, v0, 0, v167
	s_waitcnt lgkmcnt(3)
	v_med3_f32 v1, v1, 0, v167
	v_med3_f32 v2, v2, 0, v167
	v_pk_mul_f32 v[0:1], v[0:1], v[206:207]
	v_med3_f32 v3, v3, 0, v167
	v_mfma_f32_32x32x16_bf16 v[224:239], v[132:135], v[190:193], v[224:239]
	v_pk_fma_f32 v[0:1], v[2:3], v[208:209], v[0:1]
	v_med3_f32 v4, v4, 0, v167
	s_waitcnt lgkmcnt(2)
	v_med3_f32 v5, v5, 0, v167
	v_pk_fma_f32 v[0:1], v[4:5], v[210:211], v[0:1]
	v_med3_f32 v6, v6, 0, v167
	v_mfma_f32_32x32x16_bf16 v[224:239], v[128:131], v[194:197], v[224:239]
	v_med3_f32 v7, v7, 0, v167
	v_pk_fma_f32 v[0:1], v[6:7], v[212:213], v[0:1]
	v_med3_f32 v8, v8, 0, v167
	s_waitcnt lgkmcnt(1)
	v_med3_f32 v9, v9, 0, v167
	v_pk_fma_f32 v[0:1], v[8:9], v[214:215], v[0:1]
	v_med3_f32 v10, v10, 0, v167
	v_mfma_f32_32x32x16_bf16 v[224:239], v[124:127], v[198:201], v[224:239]
	v_med3_f32 v11, v11, 0, v167
	v_pk_fma_f32 v[0:1], v[10:11], v[216:217], v[0:1]
	v_med3_f32 v12, v12, 0, v167
	s_waitcnt lgkmcnt(0)
	v_med3_f32 v13, v13, 0, v167
	v_pk_fma_f32 v[0:1], v[12:13], v[218:219], v[0:1]
	v_mfma_f32_32x32x16_bf16 v[224:239], v[120:123], v[202:205], v[224:239]
	v_med3_f32 v14, v14, 0, v167
	v_med3_f32 v15, v15, 0, v167
	v_pk_fma_f32 v[0:1], v[14:15], v[220:221], v[0:1]
	v_add_f32_e32 v2, v0, v1
	v_lshl_add_u64 v[0:1], v[158:159], 0, s[22:23]
	global_store_dword v[0:1], v2, off
	s_setprio 0
	ds_read_b128 v[174:177], v169 offset:384
	ds_read_b128 v[178:181], v169 offset:400
	ds_read_b128 v[182:185], v169 offset:416
	ds_read_b128 v[186:189], v169 offset:432
	s_nop 7
	v_med3_f32 v224, v224, 0, v167
	s_waitcnt lgkmcnt(3)
	v_med3_f32 v225, v225, 0, v167
	v_med3_f32 v226, v226, 0, v167
	v_pk_mul_f32 v[224:225], v[224:225], v[174:175]
	v_med3_f32 v227, v227, 0, v167
	v_pk_fma_f32 v[224:225], v[226:227], v[176:177], v[224:225]
	v_med3_f32 v228, v228, 0, v167
	s_waitcnt lgkmcnt(2)
	v_med3_f32 v229, v229, 0, v167
	v_pk_fma_f32 v[224:225], v[228:229], v[178:179], v[224:225]
	v_med3_f32 v230, v230, 0, v167
	v_med3_f32 v231, v231, 0, v167
	v_pk_fma_f32 v[224:225], v[230:231], v[180:181], v[224:225]
	v_med3_f32 v232, v232, 0, v167
	s_waitcnt lgkmcnt(1)
	v_med3_f32 v233, v233, 0, v167
	v_pk_fma_f32 v[224:225], v[232:233], v[182:183], v[224:225]
	v_med3_f32 v234, v234, 0, v167
	v_med3_f32 v235, v235, 0, v167
	v_pk_fma_f32 v[224:225], v[234:235], v[184:185], v[224:225]
	v_med3_f32 v236, v236, 0, v167
	s_waitcnt lgkmcnt(0)
	v_med3_f32 v237, v237, 0, v167
	v_pk_fma_f32 v[224:225], v[236:237], v[186:187], v[224:225]
	v_med3_f32 v238, v238, 0, v167
	v_med3_f32 v239, v239, 0, v167
	v_pk_fma_f32 v[224:225], v[238:239], v[188:189], v[224:225]
	v_add_f32_e32 v226, v224, v225
	v_lshl_add_u64 v[224:225], v[156:157], 0, s[22:23]
	global_store_dword v[224:225], v226, off
.LBB0_1512:
	s_or_b32 s21, s20, 32
	s_cmp_gt_i32 s21, s12
	s_cbranch_scc1 .LBB0_1514
	s_mov_b32 s100, 1
	ds_read_b128 v[174:177], v170 offset:12800
	ds_read_b128 v[178:181], v170 offset:12832
	ds_read_b128 v[182:185], v170 offset:12864
	ds_read_b128 v[186:189], v170 offset:12896
	ds_read_b128 v[190:193], v170 offset:12928
	ds_read_b128 v[194:197], v170 offset:12960
	ds_read_b128 v[198:201], v170 offset:12992
	ds_read_b128 v[202:205], v170 offset:13024
	s_setprio 1
	s_waitcnt lgkmcnt(7)
	v_mfma_f32_32x32x16_bf16 v[0:15], v[44:47], v[174:177], 0
	s_waitcnt lgkmcnt(6)
	v_mfma_f32_32x32x16_bf16 v[0:15], v[40:43], v[178:181], v[0:15]
	s_waitcnt lgkmcnt(5)
	v_mfma_f32_32x32x16_bf16 v[0:15], v[36:39], v[182:185], v[0:15]
	s_waitcnt lgkmcnt(4)
	v_mfma_f32_32x32x16_bf16 v[0:15], v[32:35], v[186:189], v[0:15]
	s_waitcnt lgkmcnt(3)
	v_mfma_f32_32x32x16_bf16 v[0:15], v[28:31], v[190:193], v[0:15]
	s_waitcnt lgkmcnt(2)
	v_mfma_f32_32x32x16_bf16 v[0:15], v[24:27], v[194:197], v[0:15]
	s_waitcnt lgkmcnt(1)
	v_mfma_f32_32x32x16_bf16 v[0:15], v[20:23], v[198:201], v[0:15]
	s_waitcnt lgkmcnt(0)
	v_mfma_f32_32x32x16_bf16 v[0:15], v[16:19], v[202:205], v[0:15]
	ds_read_b128 v[206:209], v169
	ds_read_b128 v[210:213], v169 offset:16
	ds_read_b128 v[214:217], v169 offset:32
	ds_read_b128 v[218:221], v169 offset:48
	v_mfma_f32_32x32x16_bf16 v[224:239], v[76:79], v[174:177], 0
	v_mfma_f32_32x32x16_bf16 v[224:239], v[72:75], v[178:181], v[224:239]
	v_mfma_f32_32x32x16_bf16 v[224:239], v[68:71], v[182:185], v[224:239]
	v_mfma_f32_32x32x16_bf16 v[224:239], v[64:67], v[186:189], v[224:239]
	s_nop 3
	v_med3_f32 v0, v0, 0, v167
	s_waitcnt lgkmcnt(3)
	v_med3_f32 v1, v1, 0, v167
	v_med3_f32 v2, v2, 0, v167
	v_pk_mul_f32 v[0:1], v[0:1], v[206:207]
	v_med3_f32 v3, v3, 0, v167
	v_mfma_f32_32x32x16_bf16 v[224:239], v[60:63], v[190:193], v[224:239]
	v_pk_fma_f32 v[0:1], v[2:3], v[208:209], v[0:1]
	v_med3_f32 v4, v4, 0, v167
	s_waitcnt lgkmcnt(2)
; #define LAS __attribute__((address_space(3)))
; #define IX_PF_LOAD(h_) do { if (more) { _Pragma("unroll") for (int it = 0; it < 2; ++it) { const int ci = tid + 512 * (2 * (h_) + it), row = ci >> 4, ch = ci & 15; st[it] = *(const v4u*)(KIB + (size_t)(128 * ns + row) * 128 + 8 * ch); } } } while (0)
; #define IX_PF_STORE(h_) do { if (more) { _Pragma("unroll") for (int it = 0; it < 2; ++it) { const int ci = tid + 512 * (2 * (h_) + it), row = ci >> 4, ch = ci & 15; *(LAS v4u*)(NBUF + row * 272 + 16 * ch) = st[it]; } } } while (0)
; #define IX_CHAIN(acc_, a_) do { _Pragma("unroll") for (int i_ = 0; i_ < 16; ++i_) acc_[i_] = 0.f; __builtin_amdgcn_s_setprio(1); _Pragma("unroll") for (int s_ = 0; s_ < 8; ++s_) acc_ = MFMA32(af[a_][s_], bfr[s_], acc_); __builtin_amdgcn_s_setprio(0); } while (0)
; DI void indexer_prompt(LAS unsigned char* lds, const bf16* QIB, const bf16* KIB, const float* WI, float* SC, int bid, int G, int tid_) {
;     ...
;         for (int bt = 0; bt < 4; ++bt) {
;             const int key0 = k0s + 32 * bt;
;             if (bt == 2) { IX_PF_STORE(0); IX_PF_LOAD(1); }
;             if (key0 <= qlast_w) {
;             bf16x8 bfr[8];
; #pragma unroll
;             for (int s_ = 0; s_ < 8; ++s_) bfr[s_] = *(const LAS bf16x8*)(SB + (32 * bt + m) * 272 + 32 * s_ + 16 * hh);
;             f32x16 accA;
;     ...
;             IX_CHAIN(accA, 0); IX_EPI(accA, 0);
;             IX_CHAIN(accA, 1); IX_EPI(accA, 1);
;             IX_CHAIN(accA, 2); IX_EPI(accA, 2);
;             IX_CHAIN(accA, 3); IX_EPI(accA, 3);
	v_med3_f32 v5, v5, 0, v167
	v_pk_fma_f32 v[0:1], v[4:5], v[210:211], v[0:1]
	v_med3_f32 v6, v6, 0, v167
	v_mfma_f32_32x32x16_bf16 v[224:239], v[56:59], v[194:197], v[224:239]
	v_med3_f32 v7, v7, 0, v167
	v_pk_fma_f32 v[0:1], v[6:7], v[212:213], v[0:1]
	v_med3_f32 v8, v8, 0, v167
	s_waitcnt lgkmcnt(1)
	v_med3_f32 v9, v9, 0, v167
	v_pk_fma_f32 v[0:1], v[8:9], v[214:215], v[0:1]
	v_med3_f32 v10, v10, 0, v167
	v_mfma_f32_32x32x16_bf16 v[224:239], v[52:55], v[198:201], v[224:239]
	v_med3_f32 v11, v11, 0, v167
	v_pk_fma_f32 v[0:1], v[10:11], v[216:217], v[0:1]
	v_med3_f32 v12, v12, 0, v167
	s_waitcnt lgkmcnt(0)
	v_med3_f32 v13, v13, 0, v167
	v_pk_fma_f32 v[0:1], v[12:13], v[218:219], v[0:1]
	v_mfma_f32_32x32x16_bf16 v[224:239], v[48:51], v[202:205], v[224:239]
	v_med3_f32 v14, v14, 0, v167
	v_med3_f32 v15, v15, 0, v167
	s_ashr_i32 s21, s20, 31
	v_pk_fma_f32 v[0:1], v[14:15], v[220:221], v[0:1]
	s_lshl_b64 s[22:23], s[20:21], 2
	v_add_f32_e32 v2, v0, v1
	v_lshl_add_u64 v[0:1], v[162:163], 0, s[22:23]
	global_store_dword v[0:1], v2, off offset:128
	ds_read_b128 v[206:209], v169 offset:128
	ds_read_b128 v[210:213], v169 offset:144
	ds_read_b128 v[214:217], v169 offset:160
	ds_read_b128 v[218:221], v169 offset:176
	v_mfma_f32_32x32x16_bf16 v[0:15], v[108:111], v[174:177], 0
	v_mfma_f32_32x32x16_bf16 v[0:15], v[104:107], v[178:181], v[0:15]
	v_mfma_f32_32x32x16_bf16 v[0:15], v[100:103], v[182:185], v[0:15]
	v_mfma_f32_32x32x16_bf16 v[0:15], v[96:99], v[186:189], v[0:15]
	s_nop 3
	v_med3_f32 v224, v224, 0, v167
	s_waitcnt lgkmcnt(3)
	v_med3_f32 v225, v225, 0, v167
	v_med3_f32 v226, v226, 0, v167
	v_pk_mul_f32 v[224:225], v[224:225], v[206:207]
	v_med3_f32 v227, v227, 0, v167
	v_mfma_f32_32x32x16_bf16 v[0:15], v[92:95], v[190:193], v[0:15]
	v_pk_fma_f32 v[224:225], v[226:227], v[208:209], v[224:225]
	v_med3_f32 v228, v228, 0, v167
	s_waitcnt lgkmcnt(2)
	v_med3_f32 v229, v229, 0, v167
	v_pk_fma_f32 v[224:225], v[228:229], v[210:211], v[224:225]
	v_med3_f32 v230, v230, 0, v167
	v_mfma_f32_32x32x16_bf16 v[0:15], v[88:91], v[194:197], v[0:15]
	v_med3_f32 v231, v231, 0, v167
	v_pk_fma_f32 v[224:225], v[230:231], v[212:213], v[224:225]
	v_med3_f32 v232, v232, 0, v167
	s_waitcnt lgkmcnt(1)
	v_med3_f32 v233, v233, 0, v167
	v_pk_fma_f32 v[224:225], v[232:233], v[214:215], v[224:225]
	v_med3_f32 v234, v234, 0, v167
	v_mfma_f32_32x32x16_bf16 v[0:15], v[84:87], v[198:201], v[0:15]
	v_med3_f32 v235, v235, 0, v167
	v_pk_fma_f32 v[224:225], v[234:235], v[216:217], v[224:225]
	v_med3_f32 v236, v236, 0, v167
	s_waitcnt lgkmcnt(0)
	v_med3_f32 v237, v237, 0, v167
	v_pk_fma_f32 v[224:225], v[236:237], v[218:219], v[224:225]
	v_mfma_f32_32x32x16_bf16 v[0:15], v[80:83], v[202:205], v[0:15]
	v_med3_f32 v238, v238, 0, v167
	v_med3_f32 v239, v239, 0, v167
	v_pk_fma_f32 v[224:225], v[238:239], v[220:221], v[224:225]
	v_add_f32_e32 v226, v224, v225
	v_lshl_add_u64 v[224:225], v[160:161], 0, s[22:23]
	global_store_dword v[224:225], v226, off offset:128
	ds_read_b128 v[206:209], v169 offset:256
	ds_read_b128 v[210:213], v169 offset:272
	ds_read_b128 v[214:217], v169 offset:288
	ds_read_b128 v[218:221], v169 offset:304
	v_mfma_f32_32x32x16_bf16 v[224:239], v[148:151], v[174:177], 0
	v_mfma_f32_32x32x16_bf16 v[224:239], v[144:147], v[178:181], v[224:239]
	v_mfma_f32_32x32x16_bf16 v[224:239], v[140:143], v[182:185], v[224:239]
	v_mfma_f32_32x32x16_bf16 v[224:239], v[136:139], v[186:189], v[224:239]
	s_nop 3
	v_med3_f32 v0, v0, 0, v167
	s_waitcnt lgkmcnt(3)
	v_med3_f32 v1, v1, 0, v167
	v_med3_f32 v2, v2, 0, v167
	v_pk_mul_f32 v[0:1], v[0:1], v[206:207]
	v_med3_f32 v3, v3, 0, v167
	v_mfma_f32_32x32x16_bf16 v[224:239], v[132:135], v[190:193], v[224:239]
	v_pk_fma_f32 v[0:1], v[2:3], v[208:209], v[0:1]
	v_med3_f32 v4, v4, 0, v167
	s_waitcnt lgkmcnt(2)
	v_med3_f32 v5, v5, 0, v167
	v_pk_fma_f32 v[0:1], v[4:5], v[210:211], v[0:1]
	v_med3_f32 v6, v6, 0, v167
	v_mfma_f32_32x32x16_bf16 v[224:239], v[128:131], v[194:197], v[224:239]
	v_med3_f32 v7, v7, 0, v167
	v_pk_fma_f32 v[0:1], v[6:7], v[212:213], v[0:1]
	v_med3_f32 v8, v8, 0, v167
	s_waitcnt lgkmcnt(1)
	v_med3_f32 v9, v9, 0, v167
	v_pk_fma_f32 v[0:1], v[8:9], v[214:215], v[0:1]
	v_med3_f32 v10, v10, 0, v167
	v_mfma_f32_32x32x16_bf16 v[224:239], v[124:127], v[198:201], v[224:239]
	v_med3_f32 v11, v11, 0, v167
	v_pk_fma_f32 v[0:1], v[10:11], v[216:217], v[0:1]
	v_med3_f32 v12, v12, 0, v167
	s_waitcnt lgkmcnt(0)
	v_med3_f32 v13, v13, 0, v167
	v_pk_fma_f32 v[0:1], v[12:13], v[218:219], v[0:1]
	v_mfma_f32_32x32x16_bf16 v[224:239], v[120:123], v[202:205], v[224:239]
	v_med3_f32 v14, v14, 0, v167
	v_med3_f32 v15, v15, 0, v167
	v_pk_fma_f32 v[0:1], v[14:15], v[220:221], v[0:1]
	v_add_f32_e32 v2, v0, v1
	v_lshl_add_u64 v[0:1], v[158:159], 0, s[22:23]
	global_store_dword v[0:1], v2, off offset:128
	s_setprio 0
	ds_read_b128 v[174:177], v169 offset:384
	ds_read_b128 v[178:181], v169 offset:400
	ds_read_b128 v[182:185], v169 offset:416
	ds_read_b128 v[186:189], v169 offset:432
	s_nop 7
	v_med3_f32 v224, v224, 0, v167
	s_waitcnt lgkmcnt(3)
	v_med3_f32 v225, v225, 0, v167
	v_med3_f32 v226, v226, 0, v167
	v_pk_mul_f32 v[224:225], v[224:225], v[174:175]
	v_med3_f32 v227, v227, 0, v167
	v_pk_fma_f32 v[224:225], v[226:227], v[176:177], v[224:225]
	v_med3_f32 v228, v228, 0, v167
	s_waitcnt lgkmcnt(2)
	v_med3_f32 v229, v229, 0, v167
	v_pk_fma_f32 v[224:225], v[228:229], v[178:179], v[224:225]
	v_med3_f32 v230, v230, 0, v167
	v_med3_f32 v231, v231, 0, v167
	v_pk_fma_f32 v[224:225], v[230:231], v[180:181], v[224:225]
	v_med3_f32 v232, v232, 0, v167
	s_waitcnt lgkmcnt(1)
	v_med3_f32 v233, v233, 0, v167
	v_pk_fma_f32 v[224:225], v[232:233], v[182:183], v[224:225]
	v_med3_f32 v234, v234, 0, v167
	v_med3_f32 v235, v235, 0, v167
	v_pk_fma_f32 v[224:225], v[234:235], v[184:185], v[224:225]
	v_med3_f32 v236, v236, 0, v167
	s_waitcnt lgkmcnt(0)
	v_med3_f32 v237, v237, 0, v167
	v_pk_fma_f32 v[224:225], v[236:237], v[186:187], v[224:225]
	v_med3_f32 v238, v238, 0, v167
	v_med3_f32 v239, v239, 0, v167
	v_pk_fma_f32 v[224:225], v[238:239], v[188:189], v[224:225]
	v_add_f32_e32 v226, v224, v225
	v_lshl_add_u64 v[224:225], v[156:157], 0, s[22:23]
	global_store_dword v[224:225], v226, off offset:128

; #define LAS __attribute__((address_space(3)))
; #define IX_PF_LOAD(h_) do { if (more) { _Pragma("unroll") for (int it = 0; it < 2; ++it) { const int ci = tid + 512 * (2 * (h_) + it), row = ci >> 4, ch = ci & 15; st[it] = *(const v4u*)(KIB + (size_t)(128 * ns + row) * 128 + 8 * ch); } } } while (0)
; #define IX_PF_STORE(h_) do { if (more) { _Pragma("unroll") for (int it = 0; it < 2; ++it) { const int ci = tid + 512 * (2 * (h_) + it), row = ci >> 4, ch = ci & 15; *(LAS v4u*)(NBUF + row * 272 + 16 * ch) = st[it]; } } } while (0)
; #define IX_CHAIN(acc_, a_) do { _Pragma("unroll") for (int i_ = 0; i_ < 16; ++i_) acc_[i_] = 0.f; __builtin_amdgcn_s_setprio(1); _Pragma("unroll") for (int s_ = 0; s_ < 8; ++s_) acc_ = MFMA32(af[a_][s_], bfr[s_], acc_); __builtin_amdgcn_s_setprio(0); } while (0)
; DI void indexer_prompt(LAS unsigned char* lds, const bf16* QIB, const bf16* KIB, const float* WI, float* SC, int bid, int G, int tid_) {
;     ...
;         for (int bt = 0; bt < 4; ++bt) {
;             const int key0 = k0s + 32 * bt;
;             if (bt == 2) { IX_PF_STORE(0); IX_PF_LOAD(1); }
;             if (key0 <= qlast_w) {
;             bf16x8 bfr[8];
; #pragma unroll
;             for (int s_ = 0; s_ < 8; ++s_) bfr[s_] = *(const LAS bf16x8*)(SB + (32 * bt + m) * 272 + 32 * s_ + 16 * hh);
;             f32x16 accA;
;     ...
;             IX_CHAIN(accA, 0); IX_EPI(accA, 0);
;             IX_CHAIN(accA, 1); IX_EPI(accA, 1);
;             IX_CHAIN(accA, 2); IX_EPI(accA, 2);
;             IX_CHAIN(accA, 3); IX_EPI(accA, 3);
.LBB0_1517:
	s_mov_b32 s101, 1
	ds_read_b128 v[176:179], v170 offset:30208
	ds_read_b128 v[180:183], v170 offset:30240
	ds_read_b128 v[184:187], v170 offset:30272
	ds_read_b128 v[188:191], v170 offset:30304
	ds_read_b128 v[192:195], v170 offset:30336
	ds_read_b128 v[196:199], v170 offset:30368
	ds_read_b128 v[200:203], v170 offset:30400
	ds_read_b128 v[204:207], v170 offset:30432
	s_setprio 1
	s_waitcnt lgkmcnt(7)
	v_mfma_f32_32x32x16_bf16 v[0:15], v[44:47], v[176:179], 0
	s_waitcnt lgkmcnt(6)
	v_mfma_f32_32x32x16_bf16 v[0:15], v[40:43], v[180:183], v[0:15]
	s_waitcnt lgkmcnt(5)
	v_mfma_f32_32x32x16_bf16 v[0:15], v[36:39], v[184:187], v[0:15]
	s_waitcnt lgkmcnt(4)
	v_mfma_f32_32x32x16_bf16 v[0:15], v[32:35], v[188:191], v[0:15]
	s_waitcnt lgkmcnt(3)
	v_mfma_f32_32x32x16_bf16 v[0:15], v[28:31], v[192:195], v[0:15]
	s_waitcnt lgkmcnt(2)
	v_mfma_f32_32x32x16_bf16 v[0:15], v[24:27], v[196:199], v[0:15]
	s_waitcnt lgkmcnt(1)
	v_mfma_f32_32x32x16_bf16 v[0:15], v[20:23], v[200:203], v[0:15]
	s_waitcnt lgkmcnt(0)
	v_mfma_f32_32x32x16_bf16 v[0:15], v[16:19], v[204:207], v[0:15]
	ds_read_b128 v[208:211], v169
	ds_read_b128 v[212:215], v169 offset:16
	ds_read_b128 v[216:219], v169 offset:32
	ds_read_b128 v[220:223], v169 offset:48
	v_mfma_f32_32x32x16_bf16 v[224:239], v[76:79], v[176:179], 0
	v_mfma_f32_32x32x16_bf16 v[224:239], v[72:75], v[180:183], v[224:239]
	v_mfma_f32_32x32x16_bf16 v[224:239], v[68:71], v[184:187], v[224:239]
	v_mfma_f32_32x32x16_bf16 v[224:239], v[64:67], v[188:191], v[224:239]
	s_nop 3
	v_med3_f32 v0, v0, 0, v167
	s_waitcnt lgkmcnt(3)
	v_med3_f32 v1, v1, 0, v167
	v_med3_f32 v2, v2, 0, v167
	v_pk_mul_f32 v[0:1], v[0:1], v[208:209]
	v_med3_f32 v3, v3, 0, v167
	v_mfma_f32_32x32x16_bf16 v[224:239], v[60:63], v[192:195], v[224:239]
	v_pk_fma_f32 v[0:1], v[2:3], v[210:211], v[0:1]
	v_med3_f32 v4, v4, 0, v167
	s_waitcnt lgkmcnt(2)
	v_med3_f32 v5, v5, 0, v167
	v_pk_fma_f32 v[0:1], v[4:5], v[212:213], v[0:1]
	v_med3_f32 v6, v6, 0, v167
	v_mfma_f32_32x32x16_bf16 v[224:239], v[56:59], v[196:199], v[224:239]
	v_med3_f32 v7, v7, 0, v167
	v_pk_fma_f32 v[0:1], v[6:7], v[214:215], v[0:1]
	v_med3_f32 v8, v8, 0, v167
	s_waitcnt lgkmcnt(1)
	v_med3_f32 v9, v9, 0, v167
	v_pk_fma_f32 v[0:1], v[8:9], v[216:217], v[0:1]
	v_med3_f32 v10, v10, 0, v167
	v_mfma_f32_32x32x16_bf16 v[224:239], v[52:55], v[200:203], v[224:239]
	v_med3_f32 v11, v11, 0, v167
	v_pk_fma_f32 v[0:1], v[10:11], v[218:219], v[0:1]
	v_med3_f32 v12, v12, 0, v167
	s_waitcnt lgkmcnt(0)
	v_med3_f32 v13, v13, 0, v167
	v_pk_fma_f32 v[0:1], v[12:13], v[220:221], v[0:1]
	v_mfma_f32_32x32x16_bf16 v[224:239], v[48:51], v[204:207], v[224:239]
	v_med3_f32 v14, v14, 0, v167
	v_med3_f32 v15, v15, 0, v167
	s_ashr_i32 s21, s20, 31
	v_pk_fma_f32 v[0:1], v[14:15], v[222:223], v[0:1]
	s_lshl_b64 s[20:21], s[20:21], 2
	v_add_f32_e32 v2, v0, v1
	v_lshl_add_u64 v[0:1], v[162:163], 0, s[20:21]
	global_store_dword v[0:1], v2, off offset:384
	ds_read_b128 v[162:165], v169 offset:128
	ds_read_b128 v[208:211], v169 offset:144
	ds_read_b128 v[212:215], v169 offset:160
	ds_read_b128 v[216:219], v169 offset:176
	v_mfma_f32_32x32x16_bf16 v[0:15], v[108:111], v[176:179], 0
	v_mfma_f32_32x32x16_bf16 v[0:15], v[104:107], v[180:183], v[0:15]
	v_mfma_f32_32x32x16_bf16 v[0:15], v[100:103], v[184:187], v[0:15]
	v_mfma_f32_32x32x16_bf16 v[0:15], v[96:99], v[188:191], v[0:15]
	s_nop 3
	v_med3_f32 v224, v224, 0, v167
	s_waitcnt lgkmcnt(3)
	v_med3_f32 v225, v225, 0, v167
	v_med3_f32 v226, v226, 0, v167
	v_pk_mul_f32 v[224:225], v[224:225], v[162:163]
	v_med3_f32 v227, v227, 0, v167
	v_mfma_f32_32x32x16_bf16 v[0:15], v[92:95], v[192:195], v[0:15]
	v_pk_fma_f32 v[224:225], v[226:227], v[164:165], v[224:225]
	v_med3_f32 v228, v228, 0, v167
	s_waitcnt lgkmcnt(2)
	v_med3_f32 v229, v229, 0, v167
	v_pk_fma_f32 v[224:225], v[228:229], v[208:209], v[224:225]
	v_med3_f32 v230, v230, 0, v167
	v_mfma_f32_32x32x16_bf16 v[0:15], v[88:91], v[196:199], v[0:15]
	v_med3_f32 v231, v231, 0, v167
	v_pk_fma_f32 v[224:225], v[230:231], v[210:211], v[224:225]
	v_med3_f32 v232, v232, 0, v167
	s_waitcnt lgkmcnt(1)
; #define LAS __attribute__((address_space(3)))
; #define IX_PF_LOAD(h_) do { if (more) { _Pragma("unroll") for (int it = 0; it < 2; ++it) { const int ci = tid + 512 * (2 * (h_) + it), row = ci >> 4, ch = ci & 15; st[it] = *(const v4u*)(KIB + (size_t)(128 * ns + row) * 128 + 8 * ch); } } } while (0)
; #define IX_PF_STORE(h_) do { if (more) { _Pragma("unroll") for (int it = 0; it < 2; ++it) { const int ci = tid + 512 * (2 * (h_) + it), row = ci >> 4, ch = ci & 15; *(LAS v4u*)(NBUF + row * 272 + 16 * ch) = st[it]; } } } while (0)
; #define IX_CHAIN(acc_, a_) do { _Pragma("unroll") for (int i_ = 0; i_ < 16; ++i_) acc_[i_] = 0.f; __builtin_amdgcn_s_setprio(1); _Pragma("unroll") for (int s_ = 0; s_ < 8; ++s_) acc_ = MFMA32(af[a_][s_], bfr[s_], acc_); __builtin_amdgcn_s_setprio(0); } while (0)
; DI void indexer_prompt(LAS unsigned char* lds, const bf16* QIB, const bf16* KIB, const float* WI, float* SC, int bid, int G, int tid_) {
;     ...
;         for (int bt = 0; bt < 4; ++bt) {
;             const int key0 = k0s + 32 * bt;
;             if (bt == 2) { IX_PF_STORE(0); IX_PF_LOAD(1); }
;             if (key0 <= qlast_w) {
;             bf16x8 bfr[8];
; #pragma unroll
;             for (int s_ = 0; s_ < 8; ++s_) bfr[s_] = *(const LAS bf16x8*)(SB + (32 * bt + m) * 272 + 32 * s_ + 16 * hh);
;             f32x16 accA;
;     ...
;             IX_CHAIN(accA, 0); IX_EPI(accA, 0);
;             IX_CHAIN(accA, 1); IX_EPI(accA, 1);
;             IX_CHAIN(accA, 2); IX_EPI(accA, 2);
;             IX_CHAIN(accA, 3); IX_EPI(accA, 3);
;     ...
;         __syncthreads();
;         newq = nqb != qb; if (newq) wsel ^= 1;
;         qb = nqb; s = ns;
	v_med3_f32 v233, v233, 0, v167
	v_pk_fma_f32 v[224:225], v[232:233], v[212:213], v[224:225]
	v_med3_f32 v234, v234, 0, v167
	v_mfma_f32_32x32x16_bf16 v[0:15], v[84:87], v[200:203], v[0:15]
	v_med3_f32 v235, v235, 0, v167
	v_pk_fma_f32 v[224:225], v[234:235], v[214:215], v[224:225]
	v_med3_f32 v236, v236, 0, v167
	s_waitcnt lgkmcnt(0)
	v_med3_f32 v237, v237, 0, v167
	v_pk_fma_f32 v[224:225], v[236:237], v[216:217], v[224:225]
	v_mfma_f32_32x32x16_bf16 v[0:15], v[80:83], v[204:207], v[0:15]
	v_med3_f32 v238, v238, 0, v167
	v_med3_f32 v239, v239, 0, v167
	v_pk_fma_f32 v[224:225], v[238:239], v[218:219], v[224:225]
	v_add_f32_e32 v226, v224, v225
	v_lshl_add_u64 v[224:225], v[160:161], 0, s[20:21]
	global_store_dword v[224:225], v226, off offset:384
	ds_read_b128 v[160:163], v169 offset:256
	ds_read_b128 v[208:211], v169 offset:272
	ds_read_b128 v[212:215], v169 offset:288
	ds_read_b128 v[216:219], v169 offset:304
	v_mfma_f32_32x32x16_bf16 v[224:239], v[148:151], v[176:179], 0
	v_mfma_f32_32x32x16_bf16 v[224:239], v[144:147], v[180:183], v[224:239]
	v_mfma_f32_32x32x16_bf16 v[224:239], v[140:143], v[184:187], v[224:239]
	v_mfma_f32_32x32x16_bf16 v[224:239], v[136:139], v[188:191], v[224:239]
	s_nop 3
	v_med3_f32 v0, v0, 0, v167
	s_waitcnt lgkmcnt(3)
	v_med3_f32 v1, v1, 0, v167
	v_med3_f32 v2, v2, 0, v167
	v_pk_mul_f32 v[0:1], v[0:1], v[160:161]
	v_med3_f32 v3, v3, 0, v167
	v_mfma_f32_32x32x16_bf16 v[224:239], v[132:135], v[192:195], v[224:239]
	v_pk_fma_f32 v[0:1], v[2:3], v[162:163], v[0:1]
	v_med3_f32 v4, v4, 0, v167
	s_waitcnt lgkmcnt(2)
	v_med3_f32 v5, v5, 0, v167
	v_pk_fma_f32 v[0:1], v[4:5], v[208:209], v[0:1]
	v_med3_f32 v6, v6, 0, v167
	v_mfma_f32_32x32x16_bf16 v[224:239], v[128:131], v[196:199], v[224:239]
	v_med3_f32 v7, v7, 0, v167
	v_pk_fma_f32 v[0:1], v[6:7], v[210:211], v[0:1]
	v_med3_f32 v8, v8, 0, v167
	s_waitcnt lgkmcnt(1)
	v_med3_f32 v9, v9, 0, v167
	v_pk_fma_f32 v[0:1], v[8:9], v[212:213], v[0:1]
	v_med3_f32 v10, v10, 0, v167
	v_mfma_f32_32x32x16_bf16 v[224:239], v[124:127], v[200:203], v[224:239]
	v_med3_f32 v11, v11, 0, v167
	v_pk_fma_f32 v[0:1], v[10:11], v[214:215], v[0:1]
	v_med3_f32 v12, v12, 0, v167
	s_waitcnt lgkmcnt(0)
	v_med3_f32 v13, v13, 0, v167
	v_pk_fma_f32 v[0:1], v[12:13], v[216:217], v[0:1]
	v_mfma_f32_32x32x16_bf16 v[224:239], v[120:123], v[204:207], v[224:239]
	v_med3_f32 v14, v14, 0, v167
	v_med3_f32 v15, v15, 0, v167
	v_pk_fma_f32 v[0:1], v[14:15], v[218:219], v[0:1]
	v_add_f32_e32 v2, v0, v1
	v_lshl_add_u64 v[0:1], v[158:159], 0, s[20:21]
	global_store_dword v[0:1], v2, off offset:384
	s_setprio 0
	ds_read_b128 v[158:161], v169 offset:384
	ds_read_b128 v[162:165], v169 offset:400
	ds_read_b128 v[176:179], v169 offset:416
	ds_read_b128 v[180:183], v169 offset:432
	s_nop 7
	v_med3_f32 v224, v224, 0, v167
	s_waitcnt lgkmcnt(3)
	v_med3_f32 v225, v225, 0, v167
	v_med3_f32 v226, v226, 0, v167
	v_pk_mul_f32 v[224:225], v[224:225], v[158:159]
	v_med3_f32 v227, v227, 0, v167
	v_pk_fma_f32 v[224:225], v[226:227], v[160:161], v[224:225]
	v_med3_f32 v228, v228, 0, v167
	s_waitcnt lgkmcnt(2)
	v_med3_f32 v229, v229, 0, v167
	v_pk_fma_f32 v[224:225], v[228:229], v[162:163], v[224:225]
	v_med3_f32 v230, v230, 0, v167
	v_med3_f32 v231, v231, 0, v167
	v_pk_fma_f32 v[224:225], v[230:231], v[164:165], v[224:225]
	v_med3_f32 v232, v232, 0, v167
	s_waitcnt lgkmcnt(1)
	v_med3_f32 v233, v233, 0, v167
	v_pk_fma_f32 v[224:225], v[232:233], v[176:177], v[224:225]
	v_med3_f32 v234, v234, 0, v167
	v_med3_f32 v235, v235, 0, v167
	v_pk_fma_f32 v[224:225], v[234:235], v[178:179], v[224:225]
	v_med3_f32 v236, v236, 0, v167
	s_waitcnt lgkmcnt(0)
	v_med3_f32 v237, v237, 0, v167
	v_pk_fma_f32 v[224:225], v[236:237], v[180:181], v[224:225]
	v_med3_f32 v238, v238, 0, v167
	v_med3_f32 v239, v239, 0, v167
	v_pk_fma_f32 v[224:225], v[238:239], v[182:183], v[224:225]
	v_add_f32_e32 v226, v224, v225
	v_lshl_add_u64 v[224:225], v[156:157], 0, s[20:21]
	global_store_dword v[224:225], v226, off offset:384
	s_and_b64 vcc, exec, s[16:17]
	s_cbranch_vccz .LBB0_1504
	s_branch .LBB0_1521

; #define LAS __attribute__((address_space(3)))
; #define IX_CHAIN(acc_, a_) do { _Pragma("unroll") for (int i_ = 0; i_ < 16; ++i_) acc_[i_] = 0.f; __builtin_amdgcn_s_setprio(1); _Pragma("unroll") for (int s_ = 0; s_ < 8; ++s_) acc_ = MFMA32(af[a_][s_], bfr[s_], acc_); __builtin_amdgcn_s_setprio(0); } while (0)
; DI void indexer_prompt(LAS unsigned char* lds, const bf16* QIB, const bf16* KIB, const float* WI, float* SC, int bid, int G, int tid_) {
;     ...
;             bf16x8 bfr[8];
; #pragma unroll
;             for (int s_ = 0; s_ < 8; ++s_) bfr[s_] = *(const LAS bf16x8*)(SB + (32 * bt + m) * 272 + 32 * s_ + 16 * hh);
;             f32x16 accA;
;     ...
;             IX_CHAIN(accA, 0); IX_EPI(accA, 0);
;             IX_CHAIN(accA, 1); IX_EPI(accA, 1);
;             IX_CHAIN(accA, 2); IX_EPI(accA, 2);
;             IX_CHAIN(accA, 3); IX_EPI(accA, 3);
.LBB0_1519:
	ds_read_b128 v[176:179], v170 offset:21504
	ds_read_b128 v[180:183], v170 offset:21536
	ds_read_b128 v[184:187], v170 offset:21568
	ds_read_b128 v[188:191], v170 offset:21600
	ds_read_b128 v[192:195], v170 offset:21632
	ds_read_b128 v[196:199], v170 offset:21664
	ds_read_b128 v[200:203], v170 offset:21696
	ds_read_b128 v[204:207], v170 offset:21728
	s_setprio 1
	s_waitcnt lgkmcnt(7)
	v_mfma_f32_32x32x16_bf16 v[0:15], v[44:47], v[176:179], 0
	s_waitcnt lgkmcnt(6)
	v_mfma_f32_32x32x16_bf16 v[0:15], v[40:43], v[180:183], v[0:15]
	s_waitcnt lgkmcnt(5)
	v_mfma_f32_32x32x16_bf16 v[0:15], v[36:39], v[184:187], v[0:15]
	s_waitcnt lgkmcnt(4)
	v_mfma_f32_32x32x16_bf16 v[0:15], v[32:35], v[188:191], v[0:15]
	s_waitcnt lgkmcnt(3)
	v_mfma_f32_32x32x16_bf16 v[0:15], v[28:31], v[192:195], v[0:15]
	s_waitcnt lgkmcnt(2)
	v_mfma_f32_32x32x16_bf16 v[0:15], v[24:27], v[196:199], v[0:15]
	s_waitcnt lgkmcnt(1)
	v_mfma_f32_32x32x16_bf16 v[0:15], v[20:23], v[200:203], v[0:15]
	s_waitcnt lgkmcnt(0)
	v_mfma_f32_32x32x16_bf16 v[0:15], v[16:19], v[204:207], v[0:15]
	ds_read_b128 v[208:211], v169
	ds_read_b128 v[212:215], v169 offset:16
	ds_read_b128 v[216:219], v169 offset:32
	ds_read_b128 v[220:223], v169 offset:48
	v_mfma_f32_32x32x16_bf16 v[224:239], v[76:79], v[176:179], 0
	v_mfma_f32_32x32x16_bf16 v[224:239], v[72:75], v[180:183], v[224:239]
	v_mfma_f32_32x32x16_bf16 v[224:239], v[68:71], v[184:187], v[224:239]
	v_mfma_f32_32x32x16_bf16 v[224:239], v[64:67], v[188:191], v[224:239]
	s_nop 3
	v_med3_f32 v0, v0, 0, v167
	s_waitcnt lgkmcnt(3)
	v_med3_f32 v1, v1, 0, v167
	v_med3_f32 v2, v2, 0, v167
	v_pk_mul_f32 v[0:1], v[0:1], v[208:209]
	v_med3_f32 v3, v3, 0, v167
	v_mfma_f32_32x32x16_bf16 v[224:239], v[60:63], v[192:195], v[224:239]
	v_pk_fma_f32 v[0:1], v[2:3], v[210:211], v[0:1]
	v_med3_f32 v4, v4, 0, v167
	s_waitcnt lgkmcnt(2)
	v_med3_f32 v5, v5, 0, v167
	v_pk_fma_f32 v[0:1], v[4:5], v[212:213], v[0:1]
	v_med3_f32 v6, v6, 0, v167
	v_mfma_f32_32x32x16_bf16 v[224:239], v[56:59], v[196:199], v[224:239]
	v_med3_f32 v7, v7, 0, v167
	v_pk_fma_f32 v[0:1], v[6:7], v[214:215], v[0:1]
	v_med3_f32 v8, v8, 0, v167
	s_waitcnt lgkmcnt(1)
	v_med3_f32 v9, v9, 0, v167
	v_pk_fma_f32 v[0:1], v[8:9], v[216:217], v[0:1]
	v_med3_f32 v10, v10, 0, v167
	v_mfma_f32_32x32x16_bf16 v[224:239], v[52:55], v[200:203], v[224:239]
	v_med3_f32 v11, v11, 0, v167
	v_pk_fma_f32 v[0:1], v[10:11], v[218:219], v[0:1]
	v_med3_f32 v12, v12, 0, v167
	s_waitcnt lgkmcnt(0)
	v_med3_f32 v13, v13, 0, v167
	v_pk_fma_f32 v[0:1], v[12:13], v[220:221], v[0:1]
	v_mfma_f32_32x32x16_bf16 v[224:239], v[48:51], v[204:207], v[224:239]
	v_med3_f32 v14, v14, 0, v167
	v_med3_f32 v15, v15, 0, v167
	s_ashr_i32 s21, s20, 31
	v_pk_fma_f32 v[0:1], v[14:15], v[222:223], v[0:1]
	s_lshl_b64 s[22:23], s[20:21], 2
	v_add_f32_e32 v2, v0, v1
	v_lshl_add_u64 v[0:1], v[162:163], 0, s[22:23]
	global_store_dword v[0:1], v2, off offset:256
	ds_read_b128 v[208:211], v169 offset:128
	ds_read_b128 v[212:215], v169 offset:144
	ds_read_b128 v[216:219], v169 offset:160
	ds_read_b128 v[220:223], v169 offset:176
	v_mfma_f32_32x32x16_bf16 v[0:15], v[108:111], v[176:179], 0
	v_mfma_f32_32x32x16_bf16 v[0:15], v[104:107], v[180:183], v[0:15]
	v_mfma_f32_32x32x16_bf16 v[0:15], v[100:103], v[184:187], v[0:15]
	v_mfma_f32_32x32x16_bf16 v[0:15], v[96:99], v[188:191], v[0:15]
	s_nop 3
	v_med3_f32 v224, v224, 0, v167
	s_waitcnt lgkmcnt(3)
	v_med3_f32 v225, v225, 0, v167
	v_med3_f32 v226, v226, 0, v167
	v_pk_mul_f32 v[224:225], v[224:225], v[208:209]
	v_med3_f32 v227, v227, 0, v167
	v_mfma_f32_32x32x16_bf16 v[0:15], v[92:95], v[192:195], v[0:15]
	v_pk_fma_f32 v[224:225], v[226:227], v[210:211], v[224:225]
	v_med3_f32 v228, v228, 0, v167
	s_waitcnt lgkmcnt(2)
	v_med3_f32 v229, v229, 0, v167
	v_pk_fma_f32 v[224:225], v[228:229], v[212:213], v[224:225]
	v_med3_f32 v230, v230, 0, v167
	v_mfma_f32_32x32x16_bf16 v[0:15], v[88:91], v[196:199], v[0:15]
	v_med3_f32 v231, v231, 0, v167
	v_pk_fma_f32 v[224:225], v[230:231], v[214:215], v[224:225]
	v_med3_f32 v232, v232, 0, v167
	s_waitcnt lgkmcnt(1)
; #define LAS __attribute__((address_space(3)))
; #define IX_CHAIN(acc_, a_) do { _Pragma("unroll") for (int i_ = 0; i_ < 16; ++i_) acc_[i_] = 0.f; __builtin_amdgcn_s_setprio(1); _Pragma("unroll") for (int s_ = 0; s_ < 8; ++s_) acc_ = MFMA32(af[a_][s_], bfr[s_], acc_); __builtin_amdgcn_s_setprio(0); } while (0)
; DI void indexer_prompt(LAS unsigned char* lds, const bf16* QIB, const bf16* KIB, const float* WI, float* SC, int bid, int G, int tid_) {
;     ...
;             bf16x8 bfr[8];
; #pragma unroll
;             for (int s_ = 0; s_ < 8; ++s_) bfr[s_] = *(const LAS bf16x8*)(SB + (32 * bt + m) * 272 + 32 * s_ + 16 * hh);
;             f32x16 accA;
;     ...
;             IX_CHAIN(accA, 0); IX_EPI(accA, 0);
;             IX_CHAIN(accA, 1); IX_EPI(accA, 1);
;             IX_CHAIN(accA, 2); IX_EPI(accA, 2);
;             IX_CHAIN(accA, 3); IX_EPI(accA, 3);
	v_med3_f32 v233, v233, 0, v167
	v_pk_fma_f32 v[224:225], v[232:233], v[216:217], v[224:225]
	v_med3_f32 v234, v234, 0, v167
	v_mfma_f32_32x32x16_bf16 v[0:15], v[84:87], v[200:203], v[0:15]
	v_med3_f32 v235, v235, 0, v167
	v_pk_fma_f32 v[224:225], v[234:235], v[218:219], v[224:225]
	v_med3_f32 v236, v236, 0, v167
	s_waitcnt lgkmcnt(0)
	v_med3_f32 v237, v237, 0, v167
	v_pk_fma_f32 v[224:225], v[236:237], v[220:221], v[224:225]
	v_mfma_f32_32x32x16_bf16 v[0:15], v[80:83], v[204:207], v[0:15]
	v_med3_f32 v238, v238, 0, v167
	v_med3_f32 v239, v239, 0, v167
	v_pk_fma_f32 v[224:225], v[238:239], v[222:223], v[224:225]
	v_add_f32_e32 v226, v224, v225
	v_lshl_add_u64 v[224:225], v[160:161], 0, s[22:23]
	global_store_dword v[224:225], v226, off offset:256
	ds_read_b128 v[208:211], v169 offset:256
	ds_read_b128 v[212:215], v169 offset:272
	ds_read_b128 v[216:219], v169 offset:288
	ds_read_b128 v[220:223], v169 offset:304
	v_mfma_f32_32x32x16_bf16 v[224:239], v[148:151], v[176:179], 0
	v_mfma_f32_32x32x16_bf16 v[224:239], v[144:147], v[180:183], v[224:239]
	v_mfma_f32_32x32x16_bf16 v[224:239], v[140:143], v[184:187], v[224:239]
	v_mfma_f32_32x32x16_bf16 v[224:239], v[136:139], v[188:191], v[224:239]
	s_nop 3
	v_med3_f32 v0, v0, 0, v167
	s_waitcnt lgkmcnt(3)
	v_med3_f32 v1, v1, 0, v167
	v_med3_f32 v2, v2, 0, v167
	v_pk_mul_f32 v[0:1], v[0:1], v[208:209]
	v_med3_f32 v3, v3, 0, v167
	v_mfma_f32_32x32x16_bf16 v[224:239], v[132:135], v[192:195], v[224:239]
	v_pk_fma_f32 v[0:1], v[2:3], v[210:211], v[0:1]
	v_med3_f32 v4, v4, 0, v167
	s_waitcnt lgkmcnt(2)
	v_med3_f32 v5, v5, 0, v167
	v_pk_fma_f32 v[0:1], v[4:5], v[212:213], v[0:1]
	v_med3_f32 v6, v6, 0, v167
	v_mfma_f32_32x32x16_bf16 v[224:239], v[128:131], v[196:199], v[224:239]
	v_med3_f32 v7, v7, 0, v167
	v_pk_fma_f32 v[0:1], v[6:7], v[214:215], v[0:1]
	v_med3_f32 v8, v8, 0, v167
	s_waitcnt lgkmcnt(1)
	v_med3_f32 v9, v9, 0, v167
	v_pk_fma_f32 v[0:1], v[8:9], v[216:217], v[0:1]
	v_med3_f32 v10, v10, 0, v167
	v_mfma_f32_32x32x16_bf16 v[224:239], v[124:127], v[200:203], v[224:239]
	v_med3_f32 v11, v11, 0, v167
	v_pk_fma_f32 v[0:1], v[10:11], v[218:219], v[0:1]
	v_med3_f32 v12, v12, 0, v167
	s_waitcnt lgkmcnt(0)
	v_med3_f32 v13, v13, 0, v167
	v_pk_fma_f32 v[0:1], v[12:13], v[220:221], v[0:1]
	v_mfma_f32_32x32x16_bf16 v[224:239], v[120:123], v[204:207], v[224:239]
	v_med3_f32 v14, v14, 0, v167
	v_med3_f32 v15, v15, 0, v167
	v_pk_fma_f32 v[0:1], v[14:15], v[222:223], v[0:1]
	v_add_f32_e32 v2, v0, v1
	v_lshl_add_u64 v[0:1], v[158:159], 0, s[22:23]
	global_store_dword v[0:1], v2, off offset:256
	s_setprio 0
	ds_read_b128 v[176:179], v169 offset:384
	ds_read_b128 v[180:183], v169 offset:400
	ds_read_b128 v[184:187], v169 offset:416
	ds_read_b128 v[188:191], v169 offset:432
	s_nop 7
	v_med3_f32 v224, v224, 0, v167
	s_waitcnt lgkmcnt(3)
	v_med3_f32 v225, v225, 0, v167
	v_med3_f32 v226, v226, 0, v167
	v_pk_mul_f32 v[224:225], v[224:225], v[176:177]
	v_med3_f32 v227, v227, 0, v167
	v_pk_fma_f32 v[224:225], v[226:227], v[178:179], v[224:225]
	v_med3_f32 v228, v228, 0, v167
	s_waitcnt lgkmcnt(2)
	v_med3_f32 v229, v229, 0, v167
	v_pk_fma_f32 v[224:225], v[228:229], v[180:181], v[224:225]
	v_med3_f32 v230, v230, 0, v167
	v_med3_f32 v231, v231, 0, v167
	v_pk_fma_f32 v[224:225], v[230:231], v[182:183], v[224:225]
	v_med3_f32 v232, v232, 0, v167
	s_waitcnt lgkmcnt(1)
	v_med3_f32 v233, v233, 0, v167
	v_pk_fma_f32 v[224:225], v[232:233], v[184:185], v[224:225]
	v_med3_f32 v234, v234, 0, v167
	v_med3_f32 v235, v235, 0, v167
	v_pk_fma_f32 v[224:225], v[234:235], v[186:187], v[224:225]
	v_med3_f32 v236, v236, 0, v167
	s_waitcnt lgkmcnt(0)
	v_med3_f32 v237, v237, 0, v167
	v_pk_fma_f32 v[224:225], v[236:237], v[188:189], v[224:225]
	v_med3_f32 v238, v238, 0, v167
	v_med3_f32 v239, v239, 0, v167
	v_pk_fma_f32 v[224:225], v[238:239], v[190:191], v[224:225]
	v_add_f32_e32 v226, v224, v225
	v_lshl_add_u64 v[224:225], v[156:157], 0, s[22:23]
	global_store_dword v[224:225], v226, off offset:256
	s_or_b32 s21, s20, 0x60
	s_cmp_gt_i32 s21, s12
	s_cbranch_scc0 .LBB0_1517
